# GLA gate/row loads issued up front instead of one round trip per step; MLA one barrier per tile with half-tile offset, v_max3 tree, unpacked rescale
# speedup vs baseline: 1.0242x; 1.0076x over previous
; #define LAS __attribute__((address_space(3)))
; __device__ __forceinline__ int opq_bid() { int t = blockIdx.x; asm volatile("" : "+s"(t)); return t; }
; DI void gla_gates(const bf16_t* Urow0, const float* wg, const float* bg, int h, LAS float* tot, float (&bc)[8], float& total, int tid) {
;     const int d = tid & 63, seg = tid >> 6, col = h * 64 + d;
;     float wr[16];
; #pragma unroll
;     for (int r = 0; r < 16; ++r) wr[r] = wg[r * 256 + col];
;     const float bias = bg[col]; float run = 0.f;
; #pragma unroll
;     for (int tt = 0; tt < 8; ++tt) { const bf16_t* gl = Urow0 + (size_t)(8 * seg + tt) * OD_INP + 1952;
;         const u32x4 a0 = *(const u32x4*)gl, a1 = *(const u32x4*)(gl + 8); float z = bias;
; DI void gla_out_phase(LAS unsigned char* lds, const bf16_t* U, const float* wg, const float* bg, const float* gnorm, const float* GST, bf16_t* MIX) {
;     ...
;     for (int unit = opq_bid(); unit < 2048; unit += gridDim.x) {
;         const int c = unit & 255, bh = unit >> 8, b = bh >> 2, h = bh & 3;
;         const size_t tok0 = (size_t)b * SEQ + (size_t)c * 64;
;         const bf16_t* Urow0 = U + tok0 * OD_INP;
;         u32x4 vv[2]; gla_vt_load(vv, Urow0, h, tid);
;         bf16_t qraw[8], kraw[8]; u32x4 stv[2];
; #pragma unroll
;         for (int tt = 0; tt < 8; ++tt) { const bf16_t* row = Urow0 + (size_t)(8 * seg + tt) * OD_INP; qraw[tt] = row[h * 64 + d]; kraw[tt] = row[256 + h * 64 + d]; }
; #pragma unroll
;         for (int i = 0; i < 2; ++i) { const int id = tid + 512 * i, dk = id & 63, c8 = id >> 6; stv[i] = *(const u32x4*)((const bf16_t*)GST + ((size_t)unit * 64 + dk) * 128 + 8 * c8); }
.LBB0_324:
	s_ashr_i32 s0, s14, 10
	s_ashr_i32 s1, s0, 31
	s_lshl_b64 s[20:21], s[0:1], 14
	s_and_b32 s0, s2, 0x3fc0
	s_or_b32 s20, s20, s0
	s_bfe_u32 s3, s14, 0x20008
	s_lshl_b64 s[0:1], s[20:21], 12
	s_add_u32 s22, s76, s0
	s_addc_u32 s23, s77, s1
	v_mov_b32_e32 v51, v2
	v_lshl_add_u64 v[4:5], s[22:23], 0, v[50:51]
	v_lshl_or_b32 v51, s3, 6, v3
	s_ashr_i32 s15, s14, 31
	v_lshlrev_b32_e32 v82, 2, v51
	v_mov_b32_e32 v83, v2
	s_lshl_b64 s[0:1], s[14:15], 14
	v_lshl_add_u64 v[100:101], s[16:17], 0, v[82:83]
	v_lshl_add_u64 v[16:17], v[22:23], 0, s[0:1]
	v_add_co_u32_e64 v84, s[0:1], s13, v100
	v_lshl_add_u64 v[104:105], s[22:23], 0, v[24:25]
	s_nop 0
	v_addc_co_u32_e64 v85, s[0:1], 0, v101, s[0:1]
	v_add_co_u32_e64 v102, s[0:1], s5, v100
	global_load_dword v94, v82, s[16:17]
	global_load_dword v96, v82, s[16:17] offset:1024
	global_load_dword v89, v82, s[16:17] offset:2048
	global_load_dword v91, v82, s[16:17] offset:3072
	v_addc_co_u32_e64 v103, s[0:1], 0, v101, s[0:1]
	v_add_co_u32_e64 v100, s[0:1], s26, v100
	global_load_dword v87, v[102:103], off offset:-4096
	global_load_dword v88, v[84:85], off offset:1024
	global_load_dword v83, v[84:85], off offset:2048
	s_nop 0
	global_load_dword v84, v[84:85], off offset:3072
	s_nop 0
	global_load_dword v97, v[102:103], off
	global_load_dword v98, v[102:103], off offset:1024
	global_load_dword v93, v[102:103], off offset:2048
	global_load_dword v95, v[102:103], off offset:3072
	v_addc_co_u32_e64 v101, s[0:1], 0, v101, s[0:1]
	global_load_dword v90, v[100:101], off
	global_load_dword v92, v[100:101], off offset:1024
	global_load_dword v85, v[100:101], off offset:2048
	global_load_dword v86, v[100:101], off offset:3072
	global_load_dword v99, v82, s[18:19]
	s_nop 0
	global_load_dwordx4 v[100:103], v[104:105], off offset:3920
	s_nop 0
	global_load_dwordx4 v[104:107], v[104:105], off offset:3904
	v_lshl_add_u64 v[184:185], s[22:23], 0, v[26:27]
	global_load_dwordx4 v[120:123], v[184:185], off offset:3920
	global_load_dwordx4 v[124:127], v[184:185], off offset:3904
	v_lshl_add_u64 v[184:185], s[22:23], 0, v[28:29]
	global_load_dwordx4 v[128:131], v[184:185], off offset:3920
	global_load_dwordx4 v[132:135], v[184:185], off offset:3904
	v_lshl_add_u64 v[184:185], s[22:23], 0, v[30:31]
	global_load_dwordx4 v[136:139], v[184:185], off offset:3920
	global_load_dwordx4 v[140:143], v[184:185], off offset:3904
	v_lshl_add_u64 v[184:185], s[22:23], 0, v[32:33]
	global_load_dwordx4 v[144:147], v[184:185], off offset:3920
	global_load_dwordx4 v[148:151], v[184:185], off offset:3904
	v_lshl_add_u64 v[184:185], s[22:23], 0, v[34:35]
	global_load_dwordx4 v[152:155], v[184:185], off offset:3920
	global_load_dwordx4 v[156:159], v[184:185], off offset:3904
	v_lshl_add_u64 v[184:185], s[22:23], 0, v[36:37]
	global_load_dwordx4 v[160:163], v[184:185], off offset:3920
	global_load_dwordx4 v[164:167], v[184:185], off offset:3904
	v_lshl_add_u64 v[184:185], s[22:23], 0, v[38:39]
	global_load_dwordx4 v[176:179], v[184:185], off offset:3920
	global_load_dwordx4 v[180:183], v[184:185], off offset:3904
	s_lshl_b32 s8, s3, 8
	v_lshl_add_u64 v[6:7], v[4:5], 0, s[8:9]
	v_lshl_add_u64 v[4:5], v[6:7], 0, v[52:53]
	v_lshl_add_u64 v[8:9], v[6:7], 0, v[54:55]
	v_lshlrev_b32_e32 v6, 1, v51
	v_mov_b32_e32 v7, v2
	v_lshl_add_u64 v[6:7], s[22:23], 0, v[6:7]
	v_lshl_add_u64 v[62:63], v[6:7], 0, v[24:25]
	v_lshl_add_u64 v[60:61], v[6:7], 0, v[26:27]
	v_lshl_add_u64 v[58:59], v[6:7], 0, v[28:29]
	v_lshl_add_u64 v[20:21], v[6:7], 0, v[30:31]
	v_lshl_add_u64 v[18:19], v[6:7], 0, v[32:33]
	v_lshl_add_u64 v[14:15], v[6:7], 0, v[34:35]
	v_lshl_add_u64 v[12:13], v[6:7], 0, v[36:37]
	v_lshl_add_u64 v[6:7], v[6:7], 0, v[38:39]
	v_lshl_add_u64 v[10:11], v[16:17], 0, v[52:53]
	v_lshl_add_u64 v[16:17], v[16:17], 0, v[54:55]
	s_add_i32 s14, s14, s82
	s_add_i32 s2, s2, s4
	s_cmpk_gt_i32 s14, 0x7ff
	global_load_ushort v186, v[62:63], off
	global_load_ushort v187, v[62:63], off offset:512
	global_load_ushort v188, v[60:61], off
	global_load_ushort v189, v[60:61], off offset:512
	global_load_ushort v190, v[58:59], off
	global_load_ushort v191, v[58:59], off offset:512
	global_load_ushort v192, v[20:21], off
	global_load_ushort v193, v[20:21], off offset:512
	global_load_ushort v194, v[18:19], off
	global_load_ushort v195, v[18:19], off offset:512
	global_load_ushort v196, v[14:15], off
	global_load_ushort v197, v[14:15], off offset:512
	global_load_ushort v198, v[12:13], off
	global_load_ushort v199, v[12:13], off offset:512
	global_load_ushort v200, v[6:7], off
	global_load_ushort v201, v[6:7], off offset:512
	global_load_dwordx4 v[202:205], v[4:5], off offset:1024
	global_load_dwordx4 v[206:209], v[8:9], off offset:1024
	global_load_dwordx4 v[210:213], v[10:11], off
	global_load_dwordx4 v[214:217], v[16:17], off
	s_waitcnt vmcnt(0)
	v_and_b32_e32 v82, 0xffff0000, v100
	s_waitcnt vmcnt(0)
; DI float fexp(float x) { return __builtin_amdgcn_exp2f(x * LOG2E); }
; DI void gla_gates(const bf16_t* Urow0, const float* wg, const float* bg, int h, LAS float* tot, float (&bc)[8], float& total, int tid) {
;     ...
;     for (int tt = 0; tt < 8; ++tt) { const bf16_t* gl = Urow0 + (size_t)(8 * seg + tt) * OD_INP + 1952;
;         const u32x4 a0 = *(const u32x4*)gl, a1 = *(const u32x4*)(gl + 8); float z = bias;
; #pragma unroll
;         for (int p = 0; p < 4; ++p) { z += bflo(a0[p]) * wr[2 * p] + bfhi(a0[p]) * wr[2 * p + 1]; z += bflo(a1[p]) * wr[8 + 2 * p] + bfhi(a1[p]) * wr[9 + 2 * p]; }
;         const float ls = -(fmaxf(-z, 0.f) + __builtin_amdgcn_logf(1.f + fexp(-fabsf(z))) * 0.6931471805599453f);
;         run += ls * (1.f / 16.f); bc[tt] = run; }
	v_and_b32_e32 v57, 0xffff0000, v104
	v_lshlrev_b32_e32 v51, 16, v104
	v_mul_f32_e32 v57, v96, v57
	v_fmac_f32_e32 v57, v94, v51
	v_add_f32_e32 v51, v99, v57
	v_lshlrev_b32_e32 v57, 16, v100
	v_mul_f32_e32 v82, v98, v82
	v_fmac_f32_e32 v82, v97, v57
	v_add_f32_e32 v51, v82, v51
	v_and_b32_e32 v82, 0xffff0000, v105
	v_lshlrev_b32_e32 v57, 16, v105
	v_mul_f32_e32 v82, v91, v82
	v_fmac_f32_e32 v82, v89, v57
	v_add_f32_e32 v51, v82, v51
	v_and_b32_e32 v82, 0xffff0000, v101
	v_lshlrev_b32_e32 v57, 16, v101
	v_mul_f32_e32 v82, v95, v82
	v_fmac_f32_e32 v82, v93, v57
	v_add_f32_e32 v51, v82, v51
	v_and_b32_e32 v82, 0xffff0000, v106
	v_lshlrev_b32_e32 v57, 16, v106
	v_mul_f32_e32 v82, v88, v82
	v_fmac_f32_e32 v82, v87, v57
	v_add_f32_e32 v51, v82, v51
	v_and_b32_e32 v82, 0xffff0000, v102
	v_lshlrev_b32_e32 v57, 16, v102
	v_mul_f32_e32 v82, v92, v82
	v_fmac_f32_e32 v82, v90, v57
	v_add_f32_e32 v51, v82, v51
	v_and_b32_e32 v82, 0xffff0000, v107
	v_lshlrev_b32_e32 v57, 16, v107
	v_mul_f32_e32 v82, v84, v82
	v_fmac_f32_e32 v82, v83, v57
	v_lshl_add_u64 v[104:105], s[22:23], 0, v[26:27]
	v_add_f32_e32 v51, v82, v51
	v_lshlrev_b32_e32 v57, 16, v103
	v_and_b32_e32 v82, 0xffff0000, v103
	v_mov_b32_e32 v100, v120
	v_mov_b32_e32 v101, v121
	v_mov_b32_e32 v102, v122
	v_mov_b32_e32 v103, v123
	s_nop 0
	v_mov_b32_e32 v104, v124
	v_mov_b32_e32 v105, v125
	v_mov_b32_e32 v106, v126
	v_mov_b32_e32 v107, v127
	v_mul_f32_e32 v82, v86, v82
	v_fmac_f32_e32 v82, v85, v57
	v_add_f32_e32 v51, v82, v51
	v_max_f32_e64 v57, -v51, 0
	v_mul_f32_e64 v51, |v51|, s27
	v_exp_f32_e32 v51, v51
	s_waitcnt vmcnt(0)
	v_and_b32_e32 v82, 0xffff0000, v104
	v_add_f32_e32 v51, 1.0, v51
	v_log_f32_e32 v51, v51
	v_mul_f32_e32 v82, v96, v82
	v_fmac_f32_e32 v57, 0x3f317218, v51
	v_fma_f32 v51, v57, s28, 0
	v_lshlrev_b32_e32 v57, 16, v104
	v_fmac_f32_e32 v82, v94, v57
	v_add_f32_e32 v57, v99, v82
	v_lshlrev_b32_e32 v82, 16, v100
	v_and_b32_e32 v100, 0xffff0000, v100
	v_mul_f32_e32 v100, v98, v100
	v_fmac_f32_e32 v100, v97, v82
	v_add_f32_e32 v57, v100, v57
	v_and_b32_e32 v100, 0xffff0000, v105
	v_lshlrev_b32_e32 v82, 16, v105
	v_mul_f32_e32 v100, v91, v100
	v_fmac_f32_e32 v100, v89, v82
	v_add_f32_e32 v57, v100, v57
	v_and_b32_e32 v100, 0xffff0000, v101
	v_lshlrev_b32_e32 v82, 16, v101
	v_mul_f32_e32 v100, v95, v100
	v_fmac_f32_e32 v100, v93, v82
	v_add_f32_e32 v57, v100, v57
	v_and_b32_e32 v100, 0xffff0000, v106
	v_lshlrev_b32_e32 v82, 16, v106
	v_mul_f32_e32 v100, v88, v100
	v_fmac_f32_e32 v100, v87, v82
	v_add_f32_e32 v57, v100, v57
	v_and_b32_e32 v100, 0xffff0000, v102
	v_lshlrev_b32_e32 v82, 16, v102
	v_mul_f32_e32 v100, v92, v100
	v_fmac_f32_e32 v100, v90, v82
	v_add_f32_e32 v57, v100, v57
	v_and_b32_e32 v100, 0xffff0000, v107
	v_lshlrev_b32_e32 v82, 16, v107
	v_mul_f32_e32 v100, v84, v100
	v_fmac_f32_e32 v100, v83, v82
	v_add_f32_e32 v57, v100, v57
	v_and_b32_e32 v100, 0xffff0000, v103
	v_lshlrev_b32_e32 v82, 16, v103
	v_mul_f32_e32 v100, v86, v100
	v_fmac_f32_e32 v100, v85, v82
	v_lshl_add_u64 v[104:105], s[22:23], 0, v[28:29]
	v_add_f32_e32 v57, v100, v57
	v_mov_b32_e32 v100, v128
	v_mov_b32_e32 v101, v129
	v_mov_b32_e32 v102, v130
	v_mov_b32_e32 v103, v131
	s_nop 0
	v_mov_b32_e32 v104, v132
	v_mov_b32_e32 v105, v133
	v_mov_b32_e32 v106, v134
	v_mov_b32_e32 v107, v135
	v_max_f32_e64 v82, -v57, 0
	v_mul_f32_e64 v57, |v57|, s27
	v_exp_f32_e32 v57, v57
	s_nop 0
	v_add_f32_e32 v57, 1.0, v57
	v_log_f32_e32 v57, v57
	s_nop 0
	v_fmac_f32_e32 v82, 0x3f317218, v57
	v_fmamk_f32 v57, v82, 0xbd800000, v51
	s_waitcnt vmcnt(0)
	v_lshlrev_b32_e32 v82, 16, v104
	v_and_b32_e32 v104, 0xffff0000, v104
	v_mul_f32_e32 v104, v96, v104
	v_fmac_f32_e32 v104, v94, v82
	v_add_f32_e32 v82, v99, v104
	v_lshlrev_b32_e32 v104, 16, v100
	v_and_b32_e32 v100, 0xffff0000, v100
	v_mul_f32_e32 v100, v98, v100
	v_fmac_f32_e32 v100, v97, v104
	v_and_b32_e32 v104, 0xffff0000, v105
	v_add_f32_e32 v82, v100, v82
	v_lshlrev_b32_e32 v100, 16, v105
	v_mul_f32_e32 v104, v91, v104
	v_fmac_f32_e32 v104, v89, v100
	v_lshlrev_b32_e32 v100, 16, v101
	v_and_b32_e32 v101, 0xffff0000, v101
	v_mul_f32_e32 v101, v95, v101
	v_add_f32_e32 v82, v104, v82
	v_fmac_f32_e32 v101, v93, v100
	v_add_f32_e32 v82, v101, v82
	v_and_b32_e32 v101, 0xffff0000, v106
	v_lshlrev_b32_e32 v100, 16, v106
	v_mul_f32_e32 v101, v88, v101
	v_fmac_f32_e32 v101, v87, v100
	v_add_f32_e32 v82, v101, v82
	v_and_b32_e32 v101, 0xffff0000, v102
	v_lshlrev_b32_e32 v100, 16, v102
	v_mul_f32_e32 v101, v92, v101
	v_fmac_f32_e32 v101, v90, v100
	v_add_f32_e32 v82, v101, v82
	v_and_b32_e32 v101, 0xffff0000, v107
	v_lshlrev_b32_e32 v100, 16, v107
	v_mul_f32_e32 v101, v84, v101
	v_fmac_f32_e32 v101, v83, v100
	v_add_f32_e32 v82, v101, v82
	v_and_b32_e32 v101, 0xffff0000, v103
	v_lshlrev_b32_e32 v100, 16, v103
	v_mul_f32_e32 v101, v86, v101
	v_fmac_f32_e32 v101, v85, v100
	v_add_f32_e32 v82, v101, v82
	v_max_f32_e64 v100, -v82, 0
	v_mul_f32_e64 v82, |v82|, s27
	v_exp_f32_e32 v82, v82
	v_lshl_add_u64 v[104:105], s[22:23], 0, v[30:31]
	v_add_f32_e32 v82, 1.0, v82
	v_log_f32_e32 v82, v82
	s_nop 0
	v_fmac_f32_e32 v100, 0x3f317218, v82
	v_fmamk_f32 v82, v100, 0xbd800000, v57
	v_mov_b32_e32 v100, v136
	v_mov_b32_e32 v101, v137
	v_mov_b32_e32 v102, v138
	v_mov_b32_e32 v103, v139
	s_nop 0
	v_mov_b32_e32 v104, v140
	v_mov_b32_e32 v105, v141
	v_mov_b32_e32 v106, v142
	v_mov_b32_e32 v107, v143
	s_waitcnt vmcnt(0)
; DI float fexp(float x) { return __builtin_amdgcn_exp2f(x * LOG2E); }
; DI void gla_gates(const bf16_t* Urow0, const float* wg, const float* bg, int h, LAS float* tot, float (&bc)[8], float& total, int tid) {
;     ...
;     for (int tt = 0; tt < 8; ++tt) { const bf16_t* gl = Urow0 + (size_t)(8 * seg + tt) * OD_INP + 1952;
;         const u32x4 a0 = *(const u32x4*)gl, a1 = *(const u32x4*)(gl + 8); float z = bias;
; #pragma unroll
;         for (int p = 0; p < 4; ++p) { z += bflo(a0[p]) * wr[2 * p] + bfhi(a0[p]) * wr[2 * p + 1]; z += bflo(a1[p]) * wr[8 + 2 * p] + bfhi(a1[p]) * wr[9 + 2 * p]; }
;         const float ls = -(fmaxf(-z, 0.f) + __builtin_amdgcn_logf(1.f + fexp(-fabsf(z))) * 0.6931471805599453f);
;         run += ls * (1.f / 16.f); bc[tt] = run; }
	v_lshlrev_b32_e32 v108, 16, v104
	v_and_b32_e32 v104, 0xffff0000, v104
	v_mul_f32_e32 v104, v96, v104
	v_fmac_f32_e32 v104, v94, v108
	v_lshlrev_b32_e32 v108, 16, v100
	v_and_b32_e32 v100, 0xffff0000, v100
	v_mul_f32_e32 v100, v98, v100
	v_add_f32_e32 v104, v99, v104
	v_fmac_f32_e32 v100, v97, v108
	v_add_f32_e32 v100, v100, v104
	v_lshlrev_b32_e32 v104, 16, v105
	v_and_b32_e32 v105, 0xffff0000, v105
	v_mul_f32_e32 v105, v91, v105
	v_fmac_f32_e32 v105, v89, v104
	v_lshlrev_b32_e32 v104, 16, v101
	v_and_b32_e32 v101, 0xffff0000, v101
	v_mul_f32_e32 v101, v95, v101
	v_add_f32_e32 v100, v105, v100
	v_fmac_f32_e32 v101, v93, v104
	v_and_b32_e32 v104, 0xffff0000, v106
	v_add_f32_e32 v100, v101, v100
	v_lshlrev_b32_e32 v101, 16, v106
	v_mul_f32_e32 v104, v88, v104
	v_fmac_f32_e32 v104, v87, v101
	v_lshlrev_b32_e32 v101, 16, v102
	v_and_b32_e32 v102, 0xffff0000, v102
	v_mul_f32_e32 v102, v92, v102
	v_add_f32_e32 v100, v104, v100
	v_fmac_f32_e32 v102, v90, v101
	v_add_f32_e32 v100, v102, v100
	v_and_b32_e32 v102, 0xffff0000, v107
	v_lshlrev_b32_e32 v101, 16, v107
	v_mul_f32_e32 v102, v84, v102
	v_fmac_f32_e32 v102, v83, v101
	v_add_f32_e32 v100, v102, v100
	v_and_b32_e32 v102, 0xffff0000, v103
	v_lshlrev_b32_e32 v101, 16, v103
	v_mul_f32_e32 v102, v86, v102
	v_fmac_f32_e32 v102, v85, v101
	v_lshl_add_u64 v[106:107], s[22:23], 0, v[32:33]
	v_add_f32_e32 v100, v102, v100
	v_mov_b32_e32 v102, v144
	v_mov_b32_e32 v103, v145
	v_mov_b32_e32 v104, v146
	v_mov_b32_e32 v105, v147
	s_nop 0
	v_mov_b32_e32 v106, v148
	v_mov_b32_e32 v107, v149
	v_mov_b32_e32 v108, v150
	v_mov_b32_e32 v109, v151
	v_max_f32_e64 v101, -v100, 0
	v_mul_f32_e64 v100, |v100|, s27
	v_exp_f32_e32 v100, v100
	s_nop 0
	v_add_f32_e32 v100, 1.0, v100
	v_log_f32_e32 v100, v100
	s_nop 0
	v_fmac_f32_e32 v101, 0x3f317218, v100
	v_fmamk_f32 v100, v101, 0xbd800000, v82
	s_waitcnt vmcnt(0)
	v_lshlrev_b32_e32 v101, 16, v106
	v_and_b32_e32 v106, 0xffff0000, v106
	v_mul_f32_e32 v106, v96, v106
	v_fmac_f32_e32 v106, v94, v101
	v_add_f32_e32 v101, v99, v106
	v_lshlrev_b32_e32 v106, 16, v102
	v_and_b32_e32 v102, 0xffff0000, v102
	v_mul_f32_e32 v102, v98, v102
	v_fmac_f32_e32 v102, v97, v106
	v_and_b32_e32 v106, 0xffff0000, v107
	v_add_f32_e32 v101, v102, v101
	v_lshlrev_b32_e32 v102, 16, v107
	v_mul_f32_e32 v106, v91, v106
	v_fmac_f32_e32 v106, v89, v102
	v_lshlrev_b32_e32 v102, 16, v103
	v_and_b32_e32 v103, 0xffff0000, v103
	v_mul_f32_e32 v103, v95, v103
	v_add_f32_e32 v101, v106, v101
	v_fmac_f32_e32 v103, v93, v102
	v_add_f32_e32 v101, v103, v101
	v_and_b32_e32 v103, 0xffff0000, v108
	v_lshlrev_b32_e32 v102, 16, v108
	v_mul_f32_e32 v103, v88, v103
	v_fmac_f32_e32 v103, v87, v102
	v_add_f32_e32 v101, v103, v101
	v_and_b32_e32 v103, 0xffff0000, v104
	v_lshlrev_b32_e32 v102, 16, v104
	v_mul_f32_e32 v103, v92, v103
	v_fmac_f32_e32 v103, v90, v102
	v_add_f32_e32 v101, v103, v101
	v_and_b32_e32 v103, 0xffff0000, v109
	v_lshlrev_b32_e32 v102, 16, v109
	v_mul_f32_e32 v103, v84, v103
	v_fmac_f32_e32 v103, v83, v102
	v_add_f32_e32 v101, v103, v101
	v_and_b32_e32 v103, 0xffff0000, v105
	v_lshlrev_b32_e32 v102, 16, v105
	v_mul_f32_e32 v103, v86, v103
	v_fmac_f32_e32 v103, v85, v102
	v_add_f32_e32 v101, v103, v101
	v_max_f32_e64 v102, -v101, 0
	v_mul_f32_e64 v101, |v101|, s27
	v_exp_f32_e32 v101, v101
	v_lshl_add_u64 v[106:107], s[22:23], 0, v[34:35]
	v_add_f32_e32 v101, 1.0, v101
	v_log_f32_e32 v101, v101
	s_nop 0
	v_fmac_f32_e32 v102, 0x3f317218, v101
	v_fmamk_f32 v101, v102, 0xbd800000, v100
	v_mov_b32_e32 v102, v152
	v_mov_b32_e32 v103, v153
	v_mov_b32_e32 v104, v154
	v_mov_b32_e32 v105, v155
	s_nop 0
	v_mov_b32_e32 v106, v156
	v_mov_b32_e32 v107, v157
	v_mov_b32_e32 v108, v158
	v_mov_b32_e32 v109, v159
	s_waitcnt vmcnt(0)
	v_lshlrev_b32_e32 v110, 16, v106
	v_and_b32_e32 v106, 0xffff0000, v106
	v_mul_f32_e32 v106, v96, v106
	v_fmac_f32_e32 v106, v94, v110
	v_lshlrev_b32_e32 v110, 16, v102
	v_and_b32_e32 v102, 0xffff0000, v102
	v_mul_f32_e32 v102, v98, v102
	v_add_f32_e32 v106, v99, v106
	v_fmac_f32_e32 v102, v97, v110
	v_add_f32_e32 v102, v102, v106
	v_lshlrev_b32_e32 v106, 16, v107
	v_and_b32_e32 v107, 0xffff0000, v107
	v_mul_f32_e32 v107, v91, v107
	v_fmac_f32_e32 v107, v89, v106
	v_lshlrev_b32_e32 v106, 16, v103
	v_and_b32_e32 v103, 0xffff0000, v103
	v_mul_f32_e32 v103, v95, v103
	v_add_f32_e32 v102, v107, v102
	v_fmac_f32_e32 v103, v93, v106
	v_and_b32_e32 v106, 0xffff0000, v108
	v_add_f32_e32 v102, v103, v102
	v_lshlrev_b32_e32 v103, 16, v108
	v_mul_f32_e32 v106, v88, v106
	v_fmac_f32_e32 v106, v87, v103
	v_lshlrev_b32_e32 v103, 16, v104
	v_and_b32_e32 v104, 0xffff0000, v104
	v_mul_f32_e32 v104, v92, v104
	v_add_f32_e32 v102, v106, v102
	v_fmac_f32_e32 v104, v90, v103
	v_add_f32_e32 v102, v104, v102
	v_and_b32_e32 v104, 0xffff0000, v109
	v_lshlrev_b32_e32 v103, 16, v109
	v_mul_f32_e32 v104, v84, v104
	v_fmac_f32_e32 v104, v83, v103
	v_add_f32_e32 v102, v104, v102
	v_and_b32_e32 v104, 0xffff0000, v105
	v_lshlrev_b32_e32 v103, 16, v105
	v_mul_f32_e32 v104, v86, v104
	v_fmac_f32_e32 v104, v85, v103
	v_lshl_add_u64 v[108:109], s[22:23], 0, v[36:37]
	v_add_f32_e32 v102, v104, v102
	v_mov_b32_e32 v104, v160
	v_mov_b32_e32 v105, v161
	v_mov_b32_e32 v106, v162
	v_mov_b32_e32 v107, v163
	s_nop 0
	v_mov_b32_e32 v108, v164
	v_mov_b32_e32 v109, v165
	v_mov_b32_e32 v110, v166
	v_mov_b32_e32 v111, v167
	v_max_f32_e64 v103, -v102, 0
	v_mul_f32_e64 v102, |v102|, s27
	v_exp_f32_e32 v102, v102
	s_nop 0
	v_add_f32_e32 v102, 1.0, v102
	v_log_f32_e32 v102, v102
	s_nop 0
	v_fmac_f32_e32 v103, 0x3f317218, v102
	v_fmamk_f32 v102, v103, 0xbd800000, v101
	s_waitcnt vmcnt(0)
; DI float fexp(float x) { return __builtin_amdgcn_exp2f(x * LOG2E); }
; DI void gla_gates(const bf16_t* Urow0, const float* wg, const float* bg, int h, LAS float* tot, float (&bc)[8], float& total, int tid) {
;     ...
;     for (int tt = 0; tt < 8; ++tt) { const bf16_t* gl = Urow0 + (size_t)(8 * seg + tt) * OD_INP + 1952;
;         const u32x4 a0 = *(const u32x4*)gl, a1 = *(const u32x4*)(gl + 8); float z = bias;
; #pragma unroll
;         for (int p = 0; p < 4; ++p) { z += bflo(a0[p]) * wr[2 * p] + bfhi(a0[p]) * wr[2 * p + 1]; z += bflo(a1[p]) * wr[8 + 2 * p] + bfhi(a1[p]) * wr[9 + 2 * p]; }
;         const float ls = -(fmaxf(-z, 0.f) + __builtin_amdgcn_logf(1.f + fexp(-fabsf(z))) * 0.6931471805599453f);
;         run += ls * (1.f / 16.f); bc[tt] = run; }
;     tot[seg * 64 + d] = run; __syncthreads();
; DI void gla_out_phase(LAS unsigned char* lds, const bf16_t* U, const float* wg, const float* bg, const float* gnorm, const float* GST, bf16_t* MIX) {
;     ...
;         u32x4 vv[2]; gla_vt_load(vv, Urow0, h, tid);
;         bf16_t qraw[8], kraw[8]; u32x4 stv[2];
; #pragma unroll
;         for (int tt = 0; tt < 8; ++tt) { const bf16_t* row = Urow0 + (size_t)(8 * seg + tt) * OD_INP; qraw[tt] = row[h * 64 + d]; kraw[tt] = row[256 + h * 64 + d]; }
; #pragma unroll
;         for (int i = 0; i < 2; ++i) { const int id = tid + 512 * i, dk = id & 63, c8 = id >> 6; stv[i] = *(const u32x4*)((const bf16_t*)GST + ((size_t)unit * 64 + dk) * 128 + 8 * c8); }
	v_lshlrev_b32_e32 v103, 16, v108
	v_and_b32_e32 v108, 0xffff0000, v108
	v_mul_f32_e32 v108, v96, v108
	v_fmac_f32_e32 v108, v94, v103
	v_add_f32_e32 v103, v99, v108
	v_lshlrev_b32_e32 v108, 16, v104
	v_and_b32_e32 v104, 0xffff0000, v104
	v_mul_f32_e32 v104, v98, v104
	v_fmac_f32_e32 v104, v97, v108
	v_and_b32_e32 v108, 0xffff0000, v109
	v_add_f32_e32 v103, v104, v103
	v_lshlrev_b32_e32 v104, 16, v109
	v_mul_f32_e32 v108, v91, v108
	v_fmac_f32_e32 v108, v89, v104
	v_lshlrev_b32_e32 v104, 16, v105
	v_and_b32_e32 v105, 0xffff0000, v105
	v_mul_f32_e32 v105, v95, v105
	v_add_f32_e32 v103, v108, v103
	v_fmac_f32_e32 v105, v93, v104
	v_add_f32_e32 v103, v105, v103
	v_and_b32_e32 v105, 0xffff0000, v110
	v_lshlrev_b32_e32 v104, 16, v110
	v_mul_f32_e32 v105, v88, v105
	v_fmac_f32_e32 v105, v87, v104
	v_add_f32_e32 v103, v105, v103
	v_and_b32_e32 v105, 0xffff0000, v106
	v_lshlrev_b32_e32 v104, 16, v106
	v_mul_f32_e32 v105, v92, v105
	v_fmac_f32_e32 v105, v90, v104
	v_add_f32_e32 v103, v105, v103
	v_and_b32_e32 v105, 0xffff0000, v111
	v_lshlrev_b32_e32 v104, 16, v111
	v_mul_f32_e32 v105, v84, v105
	v_fmac_f32_e32 v105, v83, v104
	v_add_f32_e32 v103, v105, v103
	v_and_b32_e32 v105, 0xffff0000, v107
	v_lshlrev_b32_e32 v104, 16, v107
	v_mul_f32_e32 v105, v86, v105
	v_fmac_f32_e32 v105, v85, v104
	v_add_f32_e32 v103, v105, v103
	v_max_f32_e64 v104, -v103, 0
	v_mul_f32_e64 v103, |v103|, s27
	v_exp_f32_e32 v103, v103
	v_lshl_add_u64 v[108:109], s[22:23], 0, v[38:39]
	v_add_f32_e32 v103, 1.0, v103
	v_log_f32_e32 v103, v103
	s_nop 0
	v_fmac_f32_e32 v104, 0x3f317218, v103
	v_fmamk_f32 v103, v104, 0xbd800000, v102
	v_mov_b32_e32 v104, v176
	v_mov_b32_e32 v105, v177
	v_mov_b32_e32 v106, v178
	v_mov_b32_e32 v107, v179
	s_nop 0
	v_mov_b32_e32 v108, v180
	v_mov_b32_e32 v109, v181
	v_mov_b32_e32 v110, v182
	v_mov_b32_e32 v111, v183
	s_waitcnt vmcnt(0)
	v_lshlrev_b32_e32 v112, 16, v108
	v_and_b32_e32 v108, 0xffff0000, v108
	v_mul_f32_e32 v96, v96, v108
	v_fmac_f32_e32 v96, v94, v112
	v_add_f32_e32 v94, v99, v96
	v_and_b32_e32 v99, 0xffff0000, v104
	v_lshlrev_b32_e32 v96, 16, v104
	v_mul_f32_e32 v98, v98, v99
	v_fmac_f32_e32 v98, v97, v96
	v_and_b32_e32 v97, 0xffff0000, v109
	v_lshlrev_b32_e32 v96, 16, v109
	v_mul_f32_e32 v91, v91, v97
	v_add_f32_e32 v94, v98, v94
	v_fmac_f32_e32 v91, v89, v96
	v_add_f32_e32 v89, v91, v94
	v_and_b32_e32 v94, 0xffff0000, v105
	v_lshlrev_b32_e32 v91, 16, v105
	v_mul_f32_e32 v94, v95, v94
	v_fmac_f32_e32 v94, v93, v91
	v_and_b32_e32 v93, 0xffff0000, v110
	v_lshlrev_b32_e32 v91, 16, v110
	v_mul_f32_e32 v88, v88, v93
	v_add_f32_e32 v89, v94, v89
	v_fmac_f32_e32 v88, v87, v91
	v_add_f32_e32 v87, v88, v89
	v_and_b32_e32 v89, 0xffff0000, v106
	v_lshlrev_b32_e32 v88, 16, v106
	v_mul_f32_e32 v89, v92, v89
	v_fmac_f32_e32 v89, v90, v88
	v_add_f32_e32 v87, v89, v87
	v_and_b32_e32 v89, 0xffff0000, v111
	v_lshlrev_b32_e32 v88, 16, v111
	v_mul_f32_e32 v84, v84, v89
	v_fmac_f32_e32 v84, v83, v88
	v_add_f32_e32 v83, v84, v87
	v_and_b32_e32 v87, 0xffff0000, v107
	v_lshlrev_b32_e32 v84, 16, v107
	v_mul_f32_e32 v86, v86, v87
	v_fmac_f32_e32 v86, v85, v84
	v_add_f32_e32 v83, v86, v83
	v_max_f32_e64 v84, -v83, 0
	v_mul_f32_e64 v83, |v83|, s27
	v_exp_f32_e32 v83, v83
	s_nop 0
	v_add_f32_e32 v83, 1.0, v83
	v_log_f32_e32 v83, v83
	s_nop 0
	v_fmac_f32_e32 v84, 0x3f317218, v83
	v_fmamk_f32 v91, v84, 0xbd800000, v103
	v_mov_b32_e32 v94, v186
	v_mov_b32_e32 v90, v187
	v_mov_b32_e32 v89, v188
	v_mov_b32_e32 v88, v189
	v_mov_b32_e32 v87, v190
	v_mov_b32_e32 v86, v191
	v_mov_b32_e32 v85, v192
	v_mov_b32_e32 v84, v193
	v_mov_b32_e32 v83, v194
	v_mov_b32_e32 v63, v195
	v_mov_b32_e32 v62, v196
	v_mov_b32_e32 v61, v197
	v_mov_b32_e32 v60, v198
	v_mov_b32_e32 v59, v199
	v_mov_b32_e32 v58, v200
	v_mov_b32_e32 v21, v201
	s_nop 0
	v_mov_b32_e32 v4, v202
	v_mov_b32_e32 v5, v203
	v_mov_b32_e32 v6, v204
	v_mov_b32_e32 v7, v205
	s_nop 0
	v_mov_b32_e32 v12, v206
	v_mov_b32_e32 v13, v207
	v_mov_b32_e32 v14, v208
	v_mov_b32_e32 v15, v209
	s_nop 0
	v_mov_b32_e32 v8, v210
	v_mov_b32_e32 v9, v211
	v_mov_b32_e32 v10, v212
	v_mov_b32_e32 v11, v213
	s_nop 0
	v_mov_b32_e32 v16, v214
	v_mov_b32_e32 v17, v215
	v_mov_b32_e32 v18, v216
	v_mov_b32_e32 v19, v217
	ds_write_b32 v64, v91
	s_waitcnt lgkmcnt(0)
	s_barrier
; DI float fexp(float x) { return __builtin_amdgcn_exp2f(x * LOG2E); }
; DI void gla_gates(const bf16_t* Urow0, const float* wg, const float* bg, int h, LAS float* tot, float (&bc)[8], float& total, int tid) {
;     ...
;     float prefix = 0.f; total = 0.f;
; #pragma unroll
;     for (int s = 0; s < 8; ++s) { const float v = tot[s * 64 + d]; total += v; if (s < seg) prefix += v; }
; #pragma unroll
;     for (int tt = 0; tt < 8; ++tt) bc[tt] += prefix;
; DI void gla_out_phase(LAS unsigned char* lds, const bf16_t* U, const float* wg, const float* bg, const float* gnorm, const float* GST, bf16_t* MIX) {
;     ...
;         for (int tt = 0; tt < 8; ++tt) { const int t = 8 * seg + tt;
;             Qs[t * 72 + d] = f2bf(bf2f(qraw[tt]) * 0.125f * fexp(bc[tt])); Ks[t * 72 + d] = f2bf(bf2f(kraw[tt]) * fexp(-bc[tt])); }
;         gla_vt_store(Vt, vv, tid);
; #pragma unroll
;         for (int i = 0; i < 2; ++i) { const int id = tid + 512 * i, dk = id & 63, c8 = id >> 6;
; #pragma unroll
;             for (int e = 0; e < 8; ++e) St[(8 * c8 + e) * 72 + dk] = (bf16_t)(stv[i][e >> 1] >> (16 * (e & 1))); }
;         __syncthreads();
	ds_read2st64_b32 v[92:93], v65 offset1:1
	s_waitcnt lgkmcnt(0)
	v_add_f32_e32 v20, 0, v92
	v_cndmask_b32_e32 v20, 0, v20, vcc
	v_add_f32_e32 v92, v93, v20
	v_cndmask_b32_e64 v20, v20, v92, s[38:39]
	ds_read2st64_b32 v[92:93], v65 offset0:2 offset1:3
	s_waitcnt lgkmcnt(0)
	v_add_f32_e32 v92, v92, v20
	v_cndmask_b32_e64 v20, v20, v92, s[40:41]
	v_add_f32_e32 v92, v93, v20
	v_cndmask_b32_e64 v20, v20, v92, s[42:43]
	ds_read2st64_b32 v[92:93], v65 offset0:4 offset1:5
	s_waitcnt lgkmcnt(0)
	v_add_f32_e32 v92, v92, v20
	v_cndmask_b32_e64 v20, v20, v92, s[44:45]
	v_add_f32_e32 v92, v93, v20
	v_cndmask_b32_e64 v20, v20, v92, s[46:47]
	ds_read2st64_b32 v[92:93], v65 offset0:6 offset1:7
	s_waitcnt lgkmcnt(0)
	v_add_f32_e32 v92, v92, v20
	v_cndmask_b32_e64 v20, v20, v92, s[48:49]
	v_add_f32_e32 v92, v93, v20
	v_cndmask_b32_e64 v20, v20, v92, s[50:51]
	v_add_f32_e32 v51, v51, v20
	v_add_f32_e32 v57, v57, v20
	v_add_f32_e32 v82, v82, v20
	v_add_f32_e32 v92, v100, v20
	v_add_f32_e32 v93, v101, v20
	v_add_f32_e32 v95, v102, v20
	v_add_f32_e32 v96, v103, v20
	v_add_f32_e32 v20, v20, v91
	s_waitcnt vmcnt(19)
	v_lshlrev_b32_e32 v91, 16, v94
	v_mul_f32_e32 v94, 0x3fb8aa3b, v51
	v_mul_f32_e32 v51, 0xbfb8aa3b, v51
	v_exp_f32_e32 v51, v51
	s_waitcnt vmcnt(18)
	v_lshlrev_b32_e32 v90, 16, v90
	v_exp_f32_e32 v94, v94
	v_mul_f32_e32 v91, 0x3e000000, v91
	v_mul_f32_e32 v51, v51, v90
	v_cvt_pk_bf16_f32 v51, v51, s0
	ds_write_b16 v70, v51 offset:11264
	s_waitcnt vmcnt(17)
	v_lshlrev_b32_e32 v51, 16, v89
	v_mul_f32_e32 v89, 0x3fb8aa3b, v57
	v_exp_f32_e32 v89, v89
	v_mul_f32_e32 v57, 0xbfb8aa3b, v57
	v_mul_f32_e32 v51, 0x3e000000, v51
	v_exp_f32_e32 v57, v57
	v_mul_f32_e32 v91, v91, v94
	v_mul_f32_e32 v51, v51, v89
	v_cvt_pk_bf16_f32 v91, v91, s0
	v_cvt_pk_bf16_f32 v51, v51, s0
	ds_write_b16 v70, v91 offset:2048
	ds_write_b16 v44, v51 offset:2048
	s_waitcnt vmcnt(16)
	v_lshlrev_b32_e32 v51, 16, v88
	v_mul_f32_e32 v51, v57, v51
	v_mul_f32_e32 v57, 0x3fb8aa3b, v82
	v_exp_f32_e32 v57, v57
	v_cvt_pk_bf16_f32 v51, v51, s0
	ds_write_b16 v44, v51 offset:11264
	s_waitcnt vmcnt(15)
	v_lshlrev_b32_e32 v51, 16, v87
	v_mul_f32_e32 v51, 0x3e000000, v51
	v_mul_f32_e32 v51, v51, v57
	v_mul_f32_e32 v57, 0xbfb8aa3b, v82
	v_exp_f32_e32 v57, v57
	v_cvt_pk_bf16_f32 v51, v51, s0
	ds_write_b16 v45, v51 offset:2048
	s_waitcnt vmcnt(14)
	v_lshlrev_b32_e32 v51, 16, v86
	v_mul_f32_e32 v51, v57, v51
	v_mul_f32_e32 v57, 0x3fb8aa3b, v92
	v_exp_f32_e32 v57, v57
	v_cvt_pk_bf16_f32 v51, v51, s0
	ds_write_b16 v45, v51 offset:11264
	s_waitcnt vmcnt(13)
	v_lshlrev_b32_e32 v51, 16, v85
	v_mul_f32_e32 v51, 0x3e000000, v51
	v_mul_f32_e32 v51, v51, v57
	v_mul_f32_e32 v57, 0xbfb8aa3b, v92
	v_exp_f32_e32 v57, v57
	v_cvt_pk_bf16_f32 v51, v51, s0
	ds_write_b16 v71, v51 offset:2048
	s_waitcnt vmcnt(12)
	v_lshlrev_b32_e32 v51, 16, v84
	v_mul_f32_e32 v51, v57, v51
	v_mul_f32_e32 v57, 0x3fb8aa3b, v93
	v_exp_f32_e32 v57, v57
	v_cvt_pk_bf16_f32 v51, v51, s0
	ds_write_b16 v71, v51 offset:11264
	s_waitcnt vmcnt(11)
	v_lshlrev_b32_e32 v51, 16, v83
	v_mul_f32_e32 v51, 0x3e000000, v51
	v_mul_f32_e32 v51, v51, v57
	v_mul_f32_e32 v57, 0xbfb8aa3b, v93
	v_exp_f32_e32 v57, v57
	v_cvt_pk_bf16_f32 v51, v51, s0
	ds_write_b16 v72, v51 offset:2048
	s_waitcnt vmcnt(10)
	v_lshlrev_b32_e32 v51, 16, v63
	v_mul_f32_e32 v51, v57, v51
	v_mul_f32_e32 v57, 0x3fb8aa3b, v95
	v_exp_f32_e32 v57, v57
	v_cvt_pk_bf16_f32 v51, v51, s0
	ds_write_b16 v72, v51 offset:11264
	s_waitcnt vmcnt(9)
	v_lshlrev_b32_e32 v51, 16, v62
	v_mul_f32_e32 v51, 0x3e000000, v51
	v_mul_f32_e32 v51, v51, v57
	v_mul_f32_e32 v57, 0xbfb8aa3b, v95
	v_exp_f32_e32 v57, v57
	v_cvt_pk_bf16_f32 v51, v51, s0
	ds_write_b16 v73, v51 offset:2048
	s_waitcnt vmcnt(8)
	v_lshlrev_b32_e32 v51, 16, v61
	v_mul_f32_e32 v51, v57, v51
	v_mul_f32_e32 v57, 0x3fb8aa3b, v96
	v_exp_f32_e32 v57, v57
	v_cvt_pk_bf16_f32 v51, v51, s0
	ds_write_b16 v73, v51 offset:11264
	s_waitcnt vmcnt(7)
	v_lshlrev_b32_e32 v51, 16, v60
	v_mul_f32_e32 v51, 0x3e000000, v51
	v_mul_f32_e32 v51, v51, v57
	v_mul_f32_e32 v57, 0xbfb8aa3b, v96
	v_exp_f32_e32 v57, v57
	v_cvt_pk_bf16_f32 v51, v51, s0
	ds_write_b16 v74, v51 offset:2048
	s_waitcnt vmcnt(6)
	v_lshlrev_b32_e32 v51, 16, v59
	v_mul_f32_e32 v51, v57, v51
	v_mul_f32_e32 v57, 0x3fb8aa3b, v20
	v_mul_f32_e32 v20, 0xbfb8aa3b, v20
	v_exp_f32_e32 v57, v57
	v_exp_f32_e32 v20, v20
	v_cvt_pk_bf16_f32 v51, v51, s0
	ds_write_b16 v74, v51 offset:11264
	s_waitcnt vmcnt(5)
	v_lshlrev_b32_e32 v51, 16, v58
	v_mul_f32_e32 v51, 0x3e000000, v51
	s_waitcnt vmcnt(4)
	v_lshlrev_b32_e32 v21, 16, v21
	v_mul_f32_e32 v51, v51, v57
	v_mul_f32_e32 v20, v20, v21
	v_cvt_pk_bf16_f32 v51, v51, s0
	v_cvt_pk_bf16_f32 v20, v20, s0
	ds_write_b16 v75, v51 offset:2048
	ds_write_b16 v75, v20 offset:11264
	s_waitcnt vmcnt(3)
	ds_write_b16 v47, v4 offset:20480
	ds_write_b16_d16_hi v47, v4 offset:20624
	ds_write_b16 v47, v5 offset:20768
	ds_write_b16_d16_hi v47, v5 offset:20912
	ds_write_b16 v47, v6 offset:21056
	ds_write_b16_d16_hi v47, v6 offset:21200
	ds_write_b16 v47, v7 offset:21344
	ds_write_b16_d16_hi v49, v7 offset:20480
	s_waitcnt vmcnt(2)
	ds_write_b16 v76, v12 offset:20480
	ds_write_b16_d16_hi v76, v12 offset:20624
	ds_write_b16 v76, v13 offset:20768
	ds_write_b16_d16_hi v76, v13 offset:20912
	ds_write_b16 v76, v14 offset:21056
	ds_write_b16_d16_hi v76, v14 offset:21200
	ds_write_b16 v76, v15 offset:21344
	ds_write_b16_d16_hi v77, v15 offset:20480
	s_waitcnt vmcnt(1)
	ds_write_b16 v47, v8 offset:38912
	ds_write_b16_d16_hi v47, v8 offset:39056
	ds_write_b16 v47, v9 offset:39200
	ds_write_b16_d16_hi v47, v9 offset:39344
	ds_write_b16 v47, v10 offset:39488
	ds_write_b16_d16_hi v47, v10 offset:39632
	ds_write_b16 v47, v11 offset:39776
	ds_write_b16_d16_hi v49, v11 offset:38912
	s_waitcnt vmcnt(0)
	ds_write_b16 v76, v16 offset:38912
	ds_write_b16_d16_hi v76, v16 offset:39056
	ds_write_b16 v76, v17 offset:39200
	ds_write_b16_d16_hi v76, v17 offset:39344
	ds_write_b16 v76, v18 offset:39488
	ds_write_b16_d16_hi v76, v18 offset:39632
	ds_write_b16 v76, v19 offset:39776
	ds_write_b16_d16_hi v77, v19 offset:38912
	s_waitcnt lgkmcnt(0)
	s_barrier
; #define LAS __attribute__((address_space(3)))
; #define MFMA16(a, b, c) __builtin_amdgcn_mfma_f32_16x16x32_bf16((a), (b), (c), 0, 0, 0)
; DI void gla_out_phase(LAS unsigned char* lds, const bf16_t* U, const float* wg, const float* bg, const float* gnorm, const float* GST, bf16_t* MIX) {
;     ...
;         const int mt = w & 3;
; #pragma unroll
;         for (int j = 0; j < 2; ++j) { const int nt = (w >> 2) * 2 + j; f32x4 acc = (f32x4){0.f, 0.f, 0.f, 0.f};
; #pragma unroll
;             for (int ks = 0; ks < 2; ++ks) { const bf16x8 af = *(const LAS bf16x8*)(Qs + (16 * mt + l16) * 72 + 32 * ks + 8 * g), bfr = *(const LAS bf16x8*)(Ks + (16 * nt + l16) * 72 + 32 * ks + 8 * g); acc = MFMA16(af, bfr, acc); }
; #pragma unroll
;             for (int r = 0; r < 4; ++r) { const int t = 16 * mt + 4 * g + r, s = 16 * nt + l16; Ps[t * 72 + s] = f2bf(s <= t ? acc[r] : 0.f); } }
;         __syncthreads();
;         { f32x4 o[4];
; #pragma unroll
;           for (int j = 0; j < 4; ++j) o[j] = (f32x4){0.f, 0.f, 0.f, 0.f};
; #pragma unroll
;           for (int ks = 0; ks < 2; ++ks) { const bf16x8 aq = *(const LAS bf16x8*)(Qs + (16 * mt + l16) * 72 + 32 * ks + 8 * g), ap = *(const LAS bf16x8*)(Ps + (16 * mt + l16) * 72 + 32 * ks + 8 * g);
; #pragma unroll
;               for (int j = 0; j < 4; ++j) { const int nt = (w >> 2) * 4 + j; const bf16x8 bs = *(const LAS bf16x8*)(St + (16 * nt + l16) * 72 + 32 * ks + 8 * g), bv = *(const LAS bf16x8*)(Vt + (16 * nt + l16) * 72 + 32 * ks + 8 * g);
;                   o[j] = MFMA16(aq, bs, o[j]); o[j] = MFMA16(ap, bv, o[j]); } }
; #pragma unroll
;           for (int j = 0; j < 4; ++j) { const int nt = (w >> 2) * 4 + j;
; #pragma unroll
;               for (int r = 0; r < 4; ++r) Os[(16 * mt + 4 * g + r) * 132 + 16 * nt + l16] = o[j][r]; } }
;         __syncthreads();
	ds_read_b128 v[4:7], v66 offset:2048
	ds_read_b128 v[8:11], v78 offset:11264
	s_waitcnt lgkmcnt(0)
	v_mfma_f32_16x16x32_bf16 v[4:7], v[4:7], v[8:11], 0
	ds_read_b128 v[8:11], v66 offset:2112
	ds_read_b128 v[12:15], v78 offset:11328
	s_waitcnt lgkmcnt(0)
	v_mfma_f32_16x16x32_bf16 v[4:7], v[8:11], v[12:15], v[4:7]
	s_nop 7
	v_cvt_pk_bf16_f32 v4, v4, s0
	v_cndmask_b32_e64 v4, v4, 0, s[52:53]
	ds_write_b16 v79, v4 offset:57344
	v_cvt_pk_bf16_f32 v4, v5, s0
	v_cndmask_b32_e64 v4, v4, 0, s[54:55]
	ds_write_b16 v79, v4 offset:57488
	v_cvt_pk_bf16_f32 v4, v6, s0
	v_cndmask_b32_e64 v4, v4, 0, s[56:57]
	ds_write_b16 v79, v4 offset:57632
	v_cvt_pk_bf16_f32 v4, v7, s0
	v_cndmask_b32_e64 v4, v4, 0, s[58:59]
	ds_write_b16 v79, v4 offset:57776
	ds_read_b128 v[4:7], v66 offset:2048
	ds_read_b128 v[8:11], v78 offset:13568
	s_waitcnt lgkmcnt(0)
	v_mfma_f32_16x16x32_bf16 v[4:7], v[4:7], v[8:11], 0
	ds_read_b128 v[8:11], v66 offset:2112
	ds_read_b128 v[12:15], v78 offset:13632
	s_waitcnt lgkmcnt(0)
	v_mfma_f32_16x16x32_bf16 v[4:7], v[8:11], v[12:15], v[4:7]
	s_nop 7
	v_cvt_pk_bf16_f32 v4, v4, s0
	v_cndmask_b32_e64 v4, v4, 0, s[60:61]
	ds_write_b16 v79, v4 offset:57376
	v_cvt_pk_bf16_f32 v4, v5, s0
	v_cndmask_b32_e64 v4, v4, 0, s[62:63]
	ds_write_b16 v79, v4 offset:57520
	v_cvt_pk_bf16_f32 v4, v6, s0
	v_cndmask_b32_e64 v4, v4, 0, s[64:65]
	ds_write_b16 v79, v4 offset:57664
	v_cvt_pk_bf16_f32 v4, v7, s0
	v_cndmask_b32_e64 v4, v4, 0, s[66:67]
	ds_write_b16 v79, v4 offset:57808
	s_waitcnt lgkmcnt(0)
	s_barrier
	ds_read_b128 v[4:7], v66 offset:2048
	ds_read_b128 v[8:11], v66 offset:57344
	ds_read_b128 v[12:15], v46 offset:38912
	ds_read_b128 v[16:19], v46 offset:20480
	s_waitcnt lgkmcnt(1)
	v_mfma_f32_16x16x32_bf16 v[12:15], v[4:7], v[12:15], 0
	s_waitcnt lgkmcnt(0)
	v_mfma_f32_16x16x32_bf16 v[12:15], v[8:11], v[16:19], v[12:15]
	ds_read_b128 v[16:19], v46 offset:41216
	ds_read_b128 v[58:61], v46 offset:22784
	s_waitcnt lgkmcnt(1)
	v_mfma_f32_16x16x32_bf16 v[16:19], v[4:7], v[16:19], 0
	s_waitcnt lgkmcnt(0)
	v_mfma_f32_16x16x32_bf16 v[16:19], v[8:11], v[58:61], v[16:19]
	ds_read_b128 v[58:61], v46 offset:43520
	ds_read_b128 v[82:85], v46 offset:25088
	s_waitcnt lgkmcnt(1)
	v_mfma_f32_16x16x32_bf16 v[58:61], v[4:7], v[58:61], 0
	s_waitcnt lgkmcnt(0)
	v_mfma_f32_16x16x32_bf16 v[58:61], v[8:11], v[82:85], v[58:61]
	ds_read_b128 v[82:85], v48 offset:38912
	ds_read_b128 v[86:89], v48 offset:20480
	s_waitcnt lgkmcnt(1)
	v_mfma_f32_16x16x32_bf16 v[4:7], v[4:7], v[82:85], 0
	s_waitcnt lgkmcnt(0)
	v_mfma_f32_16x16x32_bf16 v[82:85], v[8:11], v[86:89], v[4:7]
	ds_read_b128 v[86:89], v66 offset:2112
	ds_read_b128 v[90:93], v66 offset:57408
	s_nop 3
	ds_read_b128 v[4:7], v46 offset:38976
	ds_read_b128 v[8:11], v46 offset:20544
	s_waitcnt lgkmcnt(1)
	v_mfma_f32_16x16x32_bf16 v[4:7], v[86:89], v[4:7], v[12:15]
	s_waitcnt lgkmcnt(0)
	v_mfma_f32_16x16x32_bf16 v[4:7], v[90:93], v[8:11], v[4:7]
	ds_read_b128 v[8:11], v46 offset:41280
	ds_read_b128 v[12:15], v46 offset:22848
	s_waitcnt lgkmcnt(1)
	v_mfma_f32_16x16x32_bf16 v[8:11], v[86:89], v[8:11], v[16:19]
	s_waitcnt lgkmcnt(0)
	v_mfma_f32_16x16x32_bf16 v[8:11], v[90:93], v[12:15], v[8:11]
	ds_read_b128 v[12:15], v46 offset:43584
	ds_read_b128 v[16:19], v46 offset:25152
	s_waitcnt lgkmcnt(1)
	v_mfma_f32_16x16x32_bf16 v[12:15], v[86:89], v[12:15], v[58:61]
	s_waitcnt lgkmcnt(0)
	v_mfma_f32_16x16x32_bf16 v[12:15], v[90:93], v[16:19], v[12:15]
	ds_read_b128 v[16:19], v48 offset:38976
	ds_read_b128 v[58:61], v48 offset:20544
	ds_write2_b32 v80, v4, v8 offset1:16
	ds_write2_b32 v80, v5, v9 offset0:132 offset1:148
	v_add_u32_e32 v4, 0x400, v80
	s_waitcnt lgkmcnt(3)
	v_mfma_f32_16x16x32_bf16 v[16:19], v[86:89], v[16:19], v[82:85]
	s_waitcnt lgkmcnt(2)
	v_mfma_f32_16x16x32_bf16 v[16:19], v[90:93], v[58:61], v[16:19]
	ds_write2_b32 v4, v6, v10 offset0:8 offset1:24
	ds_write2_b32 v4, v7, v11 offset0:140 offset1:156
	s_nop 5
	ds_write2_b32 v80, v12, v16 offset0:32 offset1:48
	ds_write2_b32 v80, v13, v17 offset0:164 offset1:180
	ds_write2_b32 v4, v14, v18 offset0:40 offset1:56
	ds_write2_b32 v4, v15, v19 offset0:172 offset1:188
	s_waitcnt lgkmcnt(0)
	s_barrier
; #define LAS __attribute__((address_space(3)))
; DI unsigned pk2(float lo, float hi) { const f32x2_t v = {lo, hi}; const bf16x2_t b = __builtin_convertvector(v, bf16x2_t); return __builtin_bit_cast(unsigned, b); }
; DI float silu(float x) { return x * __builtin_amdgcn_rcpf(1.f + __builtin_amdgcn_exp2f(-x * LOG2E)); }
; DI void gla_out_phase(LAS unsigned char* lds, const bf16_t* U, const float* wg, const float* bg, const float* gnorm, const float* GST, bf16_t* MIX) {
;     ...
;         { const int t = tid >> 3, part = tid & 7; f32x4 v[4]; float ss = 0.f;
; #pragma unroll
;           for (int q4 = 0; q4 < 4; ++q4) { v[q4] = *(const LAS f32x4*)(Os + t * 132 + part * 16 + 4 * q4); ss += (v[q4][0] * v[q4][0] + v[q4][1] * v[q4][1]) + (v[q4][2] * v[q4][2] + v[q4][3] * v[q4][3]); }
;           ss += __shfl_xor(ss, 1); ss += __shfl_xor(ss, 2); ss += __shfl_xor(ss, 4);
;           const float rs = __builtin_amdgcn_rsqf(ss * (1.f / 128.f) + 1e-6f);
;           const bf16_t* rrow = Urow0 + (size_t)t * OD_INP + 1024 + h * 128 + part * 16;
;           const u32x4 r0 = *(const u32x4*)rrow, r1 = *(const u32x4*)(rrow + 8);
;           u32x4 o0, o1;
; #pragma unroll
;           for (int p = 0; p < 4; ++p) { const int e0 = 2 * p, q4 = e0 >> 2, i0 = e0 & 3;
;               const f32x4 gn = *(const f32x4*)(gnorm + part * 16 + 4 * q4);
;               o0[p] = pk2(v[q4][i0] * rs * gn[i0] * silu(bflo(r0[p])), v[q4][i0 + 1] * rs * gn[i0 + 1] * silu(bfhi(r0[p])));
;               const f32x4 gn2 = *(const f32x4*)(gnorm + part * 16 + 8 + 4 * q4);
;               o1[p] = pk2(v[2 + q4][i0] * rs * gn2[i0] * silu(bflo(r1[p])), v[2 + q4][i0 + 1] * rs * gn2[i0 + 1] * silu(bfhi(r1[p]))); }
;           bf16_t* mo = MIX + (tok0 + t) * DM + h * 128 + part * 16;
;           *(u32x4*)mo = o0; *(u32x4*)(mo + 8) = o1; }
;         __syncthreads();
	ds_read_b128 v[4:7], v81
	ds_read_b128 v[14:17], v81 offset:16
	ds_read_b128 v[18:21], v81 offset:32
	ds_read_b128 v[10:13], v81 offset:48
	s_waitcnt lgkmcnt(3)
	v_pk_mul_f32 v[8:9], v[6:7], v[6:7]
	v_pk_mul_f32 v[58:59], v[4:5], v[4:5]
	s_waitcnt lgkmcnt(0)
	v_mul_f32_e32 v51, v10, v10
	v_pk_mov_b32 v[60:61], v[58:59], v[8:9] op_sel:[1,0]
	v_mov_b32_e32 v59, v9
	v_pk_add_f32 v[8:9], v[60:61], v[58:59]
	v_pk_mul_f32 v[58:59], v[16:17], v[16:17]
	v_pk_mul_f32 v[60:61], v[14:15], v[14:15]
	v_mul_f32_e32 v57, v11, v11
	v_pk_mov_b32 v[62:63], v[60:61], v[58:59] op_sel:[1,0]
	v_mov_b32_e32 v61, v59
	v_pk_add_f32 v[58:59], v[62:63], v[60:61]
	v_pk_add_f32 v[8:9], v[8:9], v[8:9] op_sel:[0,1] op_sel_hi:[1,0]
	v_pk_add_f32 v[58:59], v[58:59], v[58:59] op_sel:[0,1] op_sel_hi:[1,0]
	v_mov_b32_e32 v9, v51
	v_mov_b32_e32 v59, v57
	v_pk_add_f32 v[8:9], v[8:9], v[58:59]
	v_mul_f32_e32 v58, v19, v19
	v_mul_f32_e32 v60, v12, v12
	v_pk_fma_f32 v[58:59], v[18:19], v[18:19], v[58:59] op_sel_hi:[1,1,0]
	v_mul_f32_e32 v62, v13, v13
	v_mov_b32_e32 v59, v60
	v_mul_f32_e32 v60, v21, v21
	v_pk_fma_f32 v[60:61], v[20:21], v[20:21], v[60:61] op_sel_hi:[1,1,0]
	v_mov_b32_e32 v57, v2
	v_mov_b32_e32 v61, v62
	v_pk_add_f32 v[58:59], v[58:59], v[60:61]
	s_nop 0
	v_pk_add_f32 v[8:9], v[8:9], v[58:59]
	s_nop 0
	v_add_f32_e32 v8, v8, v9
	ds_bpermute_b32 v9, v67, v8
	s_waitcnt lgkmcnt(0)
	v_add_f32_e32 v8, v8, v9
	ds_bpermute_b32 v9, v68, v8
	s_waitcnt lgkmcnt(0)
	v_add_f32_e32 v8, v8, v9
	ds_bpermute_b32 v9, v69, v8
	s_waitcnt lgkmcnt(0)
	v_add_f32_e32 v8, v8, v9
	v_fmamk_f32 v8, v8, 0x3c000000, v174
	v_rsq_f32_e32 v58, v8
	v_lshl_add_u64 v[8:9], s[22:23], 0, v[40:41]
	v_lshl_add_u64 v[8:9], v[8:9], 0, s[8:9]
	v_lshl_add_u64 v[8:9], v[8:9], 0, v[56:57]
	global_load_dwordx4 v[60:63], v[8:9], off offset:2064
	global_load_dwordx4 v[82:85], v[8:9], off offset:2048
	global_load_dwordx4 v[86:89], v[42:43], off offset:48
	global_load_dwordx4 v[90:93], v[42:43], off offset:16
	global_load_dwordx4 v[94:97], v[42:43], off offset:32
	global_load_dwordx4 v[98:101], v[42:43], off
	v_pk_mul_f32 v[4:5], v[4:5], v[58:59] op_sel_hi:[1,0]
	v_pk_mul_f32 v[18:19], v[18:19], v[58:59] op_sel_hi:[1,0]
	v_pk_mul_f32 v[6:7], v[6:7], v[58:59] op_sel_hi:[1,0]
	v_pk_mul_f32 v[20:21], v[20:21], v[58:59] op_sel_hi:[1,0]
	v_pk_mul_f32 v[14:15], v[14:15], v[58:59] op_sel_hi:[1,0]
	v_pk_mul_f32 v[10:11], v[10:11], v[58:59] op_sel_hi:[1,0]
	v_pk_mul_f32 v[16:17], v[16:17], v[58:59] op_sel_hi:[1,0]
	v_pk_mul_f32 v[12:13], v[12:13], v[58:59] op_sel_hi:[1,0]
	s_waitcnt vmcnt(4)
	v_lshlrev_b32_e32 v8, 16, v82
	v_mul_f32_e32 v51, 0xbfb8aa3b, v8
	v_exp_f32_e32 v51, v51
	v_and_b32_e32 v9, 0xffff0000, v82
	s_waitcnt vmcnt(0)
	v_pk_mul_f32 v[4:5], v[98:99], v[4:5]
	v_pk_mul_f32 v[18:19], v[94:95], v[18:19]
	v_add_f32_e32 v51, 1.0, v51
	v_rcp_f32_e32 v102, v51
	v_mul_f32_e32 v51, 0xbfb8aa3b, v9
	v_exp_f32_e32 v51, v51
	v_pk_mul_f32 v[6:7], v[100:101], v[6:7]
	v_pk_mul_f32 v[20:21], v[96:97], v[20:21]
	v_pk_mul_f32 v[14:15], v[90:91], v[14:15]
	v_add_f32_e32 v51, 1.0, v51
	v_rcp_f32_e32 v103, v51
	v_pk_mul_f32 v[10:11], v[86:87], v[10:11]
	v_pk_mul_f32 v[16:17], v[92:93], v[16:17]
	v_pk_mul_f32 v[12:13], v[88:89], v[12:13]
	v_pk_mul_f32 v[8:9], v[102:103], v[8:9]
	s_nop 0
	v_pk_mul_f32 v[4:5], v[8:9], v[4:5]
	v_lshlrev_b32_e32 v8, 16, v60
	v_cvt_pk_bf16_f32 v4, v4, v5
	v_mul_f32_e32 v5, 0xbfb8aa3b, v8
	v_exp_f32_e32 v5, v5
	v_and_b32_e32 v9, 0xffff0000, v60
	v_add_f32_e32 v5, 1.0, v5
	v_rcp_f32_e32 v98, v5
	v_mul_f32_e32 v5, 0xbfb8aa3b, v9
	v_exp_f32_e32 v5, v5
	s_nop 0
	v_add_f32_e32 v5, 1.0, v5
	v_rcp_f32_e32 v99, v5
	s_nop 0
	v_pk_mul_f32 v[8:9], v[98:99], v[8:9]
	s_nop 0
	v_pk_mul_f32 v[8:9], v[8:9], v[18:19]
	v_lshlrev_b32_e32 v18, 16, v83
	v_mul_f32_e32 v5, 0xbfb8aa3b, v18
	v_exp_f32_e32 v5, v5
	v_and_b32_e32 v19, 0xffff0000, v83
	v_cvt_pk_bf16_f32 v8, v8, v9
	v_add_f32_e32 v5, 1.0, v5
	v_rcp_f32_e32 v82, v5
	v_mul_f32_e32 v5, 0xbfb8aa3b, v19
	v_exp_f32_e32 v5, v5
	s_nop 0
	v_add_f32_e32 v5, 1.0, v5
	v_rcp_f32_e32 v83, v5
	s_nop 0
	v_pk_mul_f32 v[18:19], v[82:83], v[18:19]
	s_nop 0
	v_pk_mul_f32 v[6:7], v[18:19], v[6:7]
	s_nop 0
	v_cvt_pk_bf16_f32 v5, v6, v7
	v_lshlrev_b32_e32 v6, 16, v61
	v_mul_f32_e32 v9, 0xbfb8aa3b, v6
	v_exp_f32_e32 v9, v9
	v_and_b32_e32 v7, 0xffff0000, v61
	v_add_f32_e32 v9, 1.0, v9
	v_rcp_f32_e32 v18, v9
	v_mul_f32_e32 v9, 0xbfb8aa3b, v7
	v_exp_f32_e32 v9, v9
	s_nop 0
	v_add_f32_e32 v9, 1.0, v9
	v_rcp_f32_e32 v19, v9
	s_nop 0
	v_pk_mul_f32 v[6:7], v[18:19], v[6:7]
	s_nop 0
	v_pk_mul_f32 v[6:7], v[6:7], v[20:21]
	s_nop 0
	v_cvt_pk_bf16_f32 v9, v6, v7
	v_lshlrev_b32_e32 v6, 16, v84
	v_and_b32_e32 v7, 0xffff0000, v84
	v_mul_f32_e32 v18, 0xbfb8aa3b, v6
	v_mul_f32_e32 v19, 0xbfb8aa3b, v7
	v_exp_f32_e32 v18, v18
	v_exp_f32_e32 v19, v19
	v_add_f32_e32 v18, 1.0, v18
	v_add_f32_e32 v19, 1.0, v19
	v_rcp_f32_e32 v18, v18
	v_rcp_f32_e32 v19, v19
	s_nop 0
	v_pk_mul_f32 v[6:7], v[18:19], v[6:7]
	s_nop 0
	v_pk_mul_f32 v[6:7], v[6:7], v[14:15]
	v_lshlrev_b32_e32 v14, 16, v62
	v_cvt_pk_bf16_f32 v6, v6, v7
	v_mul_f32_e32 v7, 0xbfb8aa3b, v14
	v_exp_f32_e32 v7, v7
	v_and_b32_e32 v15, 0xffff0000, v62
	v_add_f32_e32 v7, 1.0, v7
	v_rcp_f32_e32 v18, v7
	v_mul_f32_e32 v7, 0xbfb8aa3b, v15
	v_exp_f32_e32 v7, v7
	s_nop 0
	v_add_f32_e32 v7, 1.0, v7
	v_rcp_f32_e32 v19, v7
	s_nop 0
	v_pk_mul_f32 v[14:15], v[18:19], v[14:15]
	s_nop 0
	v_pk_mul_f32 v[10:11], v[14:15], v[10:11]
	v_lshlrev_b32_e32 v14, 16, v85
	v_mul_f32_e32 v7, 0xbfb8aa3b, v14
	v_exp_f32_e32 v7, v7
	v_and_b32_e32 v15, 0xffff0000, v85
	v_cvt_pk_bf16_f32 v10, v10, v11
	v_add_f32_e32 v7, 1.0, v7
	v_rcp_f32_e32 v18, v7
	v_mul_f32_e32 v7, 0xbfb8aa3b, v15
	v_exp_f32_e32 v7, v7
	s_nop 0
	v_add_f32_e32 v7, 1.0, v7
	v_rcp_f32_e32 v19, v7
	s_nop 0
	v_pk_mul_f32 v[14:15], v[18:19], v[14:15]
	s_nop 0
	v_pk_mul_f32 v[14:15], v[14:15], v[16:17]
	s_nop 0
	v_cvt_pk_bf16_f32 v7, v14, v15
	v_lshlrev_b32_e32 v14, 16, v63
	v_mul_f32_e32 v11, 0xbfb8aa3b, v14
	v_exp_f32_e32 v11, v11
	v_and_b32_e32 v15, 0xffff0000, v63
	v_add_f32_e32 v11, 1.0, v11
	v_rcp_f32_e32 v16, v11
	v_mul_f32_e32 v11, 0xbfb8aa3b, v15
	v_exp_f32_e32 v11, v11
	s_nop 0
	v_add_f32_e32 v11, 1.0, v11
	v_rcp_f32_e32 v17, v11
	s_nop 0
	v_pk_mul_f32 v[14:15], v[16:17], v[14:15]
	s_nop 0
	v_pk_mul_f32 v[12:13], v[14:15], v[12:13]
	s_nop 0
	v_cvt_pk_bf16_f32 v11, v12, v13
	v_lshl_add_u64 v[12:13], s[20:21], 0, v[0:1]
	v_lshlrev_b64 v[12:13], 11, v[12:13]
	v_lshl_add_u64 v[12:13], s[24:25], 0, v[12:13]
	v_lshl_add_u64 v[12:13], v[12:13], 0, s[8:9]
	v_lshl_add_u64 v[12:13], v[12:13], 0, v[56:57]
	global_store_dwordx4 v[12:13], v[4:7], off
	global_store_dwordx4 v[12:13], v[8:11], off offset:16
	s_barrier
	s_cbranch_scc0 .LBB0_324

; DI void mla_attn_phase(LAS unsigned char* lds, const bf16_t* Qg, const bf16_t* Kg, const bf16_t* Vtg, bf16_t* MIX) {
;     ...
;                     float mxa = fmaxf(s0[0], s1[0]), mxb = fmaxf(s0[1], s1[1]), mxc = fmaxf(s0[2], s1[2]), mxd = fmaxf(s0[3], s1[3]);
; #pragma unroll
;                     for (int i = 4; i < 16; i += 4) { mxa = fmaxf(mxa, fmaxf(s0[i], s1[i])); mxb = fmaxf(mxb, fmaxf(s0[i + 1], s1[i + 1])); mxc = fmaxf(mxc, fmaxf(s0[i + 2], s1[i + 2])); mxd = fmaxf(mxd, fmaxf(s0[i + 3], s1[i + 3])); }
;                     float mx = fmaxf(fmaxf(mxa, mxb), fmaxf(mxc, mxd));
;                     { const auto rr = __builtin_amdgcn_permlane32_swap(__float_as_uint(mx), __float_as_uint(mx), false, false); mx = fmaxf(__uint_as_float(rr[0]), __uint_as_float(rr[1])); }
;                     const float m_new = fmaxf(m_run, mx), alpha = __builtin_amdgcn_exp2f(m_run - m_new); m_run = m_new;
;                     float sum = 0.f;
; #pragma unroll
;                     for (int i = 0; i < 16; ++i) { s0[i] = __builtin_amdgcn_exp2f(s0[i] - m_new); s1[i] = __builtin_amdgcn_exp2f(s1[i] - m_new); sum += s0[i] + s1[i]; }
;                     l_run = l_run * alpha + sum;
;                     if (__any(alpha != 1.f)) {
; #pragma unroll
;                         for (int mt = 0; mt < 4; ++mt)
; #pragma unroll
;                             for (int i = 0; i < 16; ++i) o[mt][i] *= alpha; }
.LBB0_364:
	s_nop 4
	v_max3_f32 v0, v80, v81, v82
	v_max3_f32 v3, v83, v84, v85
	v_max3_f32 v218, v86, v87, v88
	v_max3_f32 v219, v89, v90, v91
	v_max3_f32 v0, v0, v92, v93
	v_max3_f32 v3, v3, v94, v95
	v_max3_f32 v218, v218, v96, v97
	v_max3_f32 v219, v219, v98, v99
	v_max3_f32 v0, v0, v100, v101
	v_max3_f32 v3, v3, v102, v103
	v_max3_f32 v218, v218, v104, v105
	v_max3_f32 v219, v219, v106, v107
	v_max3_f32 v0, v0, v108, v109
	v_max3_f32 v3, v3, v110, v111
	v_max3_f32 v0, v0, v3, v218
	v_max_f32_e32 v0, v0, v219
	v_mov_b32_e32 v3, v0
	s_nop 1
	v_permlane32_swap_b32_e32 v0, v3
	v_max3_f32 v3, v234, v0, v3
	v_sub_f32_e32 v0, v234, v3
	v_exp_f32_e32 v0, v0
	s_nop 0
	v_cmp_neq_f32_e32 vcc, 1.0, v0
	s_cbranch_vccz .Lmla_mid
	v_mul_f32_e32 v78, v0, v78
	v_mul_f32_e32 v79, v0, v79
	v_mul_f32_e32 v76, v0, v76
	v_mul_f32_e32 v77, v0, v77
	v_mul_f32_e32 v74, v0, v74
	v_mul_f32_e32 v75, v0, v75
	v_mul_f32_e32 v72, v0, v72
	v_mul_f32_e32 v73, v0, v73
	v_mul_f32_e32 v70, v0, v70
	v_mul_f32_e32 v71, v0, v71
	v_mul_f32_e32 v68, v0, v68
	v_mul_f32_e32 v69, v0, v69
	v_mul_f32_e32 v66, v0, v66
	v_mul_f32_e32 v67, v0, v67
	v_mul_f32_e32 v64, v0, v64
	v_mul_f32_e32 v65, v0, v65
	v_mul_f32_e32 v62, v0, v62
	v_mul_f32_e32 v63, v0, v63
	v_mul_f32_e32 v60, v0, v60
	v_mul_f32_e32 v61, v0, v61
	v_mul_f32_e32 v58, v0, v58
	v_mul_f32_e32 v59, v0, v59
	v_mul_f32_e32 v56, v0, v56
	v_mul_f32_e32 v57, v0, v57
	v_mul_f32_e32 v54, v0, v54
	v_mul_f32_e32 v55, v0, v55
	v_mul_f32_e32 v52, v0, v52
	v_mul_f32_e32 v53, v0, v53
	v_mul_f32_e32 v50, v0, v50
	v_mul_f32_e32 v51, v0, v51
	v_mul_f32_e32 v48, v0, v48
	v_mul_f32_e32 v49, v0, v49
	v_mul_f32_e32 v46, v0, v46
	v_mul_f32_e32 v47, v0, v47
	v_mul_f32_e32 v44, v0, v44
	v_mul_f32_e32 v45, v0, v45
	v_mul_f32_e32 v42, v0, v42
	v_mul_f32_e32 v43, v0, v43
	v_mul_f32_e32 v40, v0, v40
	v_mul_f32_e32 v41, v0, v41
	v_mul_f32_e32 v38, v0, v38
	v_mul_f32_e32 v39, v0, v39
	v_mul_f32_e32 v36, v0, v36
	v_mul_f32_e32 v37, v0, v37
	v_mul_f32_e32 v34, v0, v34
	v_mul_f32_e32 v35, v0, v35
	v_mul_f32_e32 v32, v0, v32
	v_mul_f32_e32 v33, v0, v33
	v_mul_f32_e32 v30, v0, v30
	v_mul_f32_e32 v31, v0, v31
	v_mul_f32_e32 v28, v0, v28
	v_mul_f32_e32 v29, v0, v29
	v_mul_f32_e32 v26, v0, v26
	v_mul_f32_e32 v27, v0, v27
	v_mul_f32_e32 v24, v0, v24
	v_mul_f32_e32 v25, v0, v25
	v_mul_f32_e32 v22, v0, v22
	v_mul_f32_e32 v23, v0, v23
	v_mul_f32_e32 v20, v0, v20
	v_mul_f32_e32 v21, v0, v21
	v_mul_f32_e32 v18, v0, v18
	v_mul_f32_e32 v19, v0, v19
	v_mul_f32_e32 v16, v0, v16
	v_mul_f32_e32 v17, v0, v17

; __device__ __forceinline__ int opq_bid() { int t = blockIdx.x; asm volatile("" : "+s"(t)); return t; }
; DI float fexp(float x) { return __builtin_amdgcn_exp2f(x * LOG2E); }
; DI void gla_gates(const bf16_t* Urow0, const float* wg, const float* bg, int h, LAS float* tot, float (&bc)[8], float& total, int tid) {
;     ...
;     float wr[16];
; #pragma unroll
;     for (int r = 0; r < 16; ++r) wr[r] = wg[r * 256 + col];
;     const float bias = bg[col]; float run = 0.f;
; #pragma unroll
;     for (int tt = 0; tt < 8; ++tt) { const bf16_t* gl = Urow0 + (size_t)(8 * seg + tt) * OD_INP + 1952;
;         const u32x4 a0 = *(const u32x4*)gl, a1 = *(const u32x4*)(gl + 8); float z = bias;
; #pragma unroll
;         for (int p = 0; p < 4; ++p) { z += bflo(a0[p]) * wr[2 * p] + bfhi(a0[p]) * wr[2 * p + 1]; z += bflo(a1[p]) * wr[8 + 2 * p] + bfhi(a1[p]) * wr[9 + 2 * p]; }
;         const float ls = -(fmaxf(-z, 0.f) + __builtin_amdgcn_logf(1.f + fexp(-fabsf(z))) * 0.6931471805599453f);
;         run += ls * (1.f / 16.f); bc[tt] = run; }
; DI void gla_local_phase(LAS unsigned char* lds, const bf16_t* U, const float* wg, const float* bg, float* GST, float* DVEC) {
;     ...
;     for (int unit = opq_bid(); unit < 2048; unit += gridDim.x) {
;         const int c = unit & 255, bh = unit >> 8, b = bh >> 2, h = bh & 3;
;         const bf16_t* Urow0 = U + ((size_t)b * SEQ + (size_t)c * 64) * OD_INP;
;         u32x4 vv[2]; gla_vt_load(vv, Urow0, h, tid);
;         bf16_t kraw[8];
; #pragma unroll
;         for (int tt = 0; tt < 8; ++tt) kraw[tt] = Urow0[(size_t)(8 * seg + tt) * OD_INP + 256 + h * 64 + d];
;         float bc[8], total; gla_gates(Urow0, wg, bg, h, tot, bc, total, tid);
.LBB0_396:
	s_ashr_i32 s0, s4, 10
	s_ashr_i32 s1, s0, 31
	s_bfe_u32 s3, s4, 0x20008
	s_and_b32 s5, s2, 0x1fe0000
	s_lshl_b64 s[0:1], s[0:1], 26
	s_add_u32 s0, s76, s0
	s_addc_u32 s1, s77, s1
	s_lshl_b32 s5, s5, 1
	s_add_u32 s18, s0, s5
	s_addc_u32 s19, s1, 0
	s_lshl_b32 s0, s3, 7
	s_lshl_b32 s8, s3, 8
	s_add_u32 s0, s18, s0
	s_addc_u32 s1, s19, 0
	v_mov_b32_e32 v51, v2
	v_lshl_add_u64 v[12:13], s[0:1], 0, v[50:51]
	v_lshl_add_u64 v[66:67], v[12:13], 0, v[24:25]
	v_lshl_add_u64 v[64:65], v[12:13], 0, v[26:27]
	v_lshl_add_u64 v[62:63], v[12:13], 0, v[28:29]
	v_lshl_add_u64 v[60:61], v[12:13], 0, v[30:31]
	v_lshl_add_u64 v[58:59], v[12:13], 0, v[32:33]
	v_lshl_add_u64 v[56:57], v[12:13], 0, v[34:35]
	v_lshl_add_u64 v[54:55], v[12:13], 0, v[36:37]
	v_lshl_add_u64 v[52:53], v[12:13], 0, v[38:39]
	v_lshl_or_b32 v12, v0, 2, s8
	v_mov_b32_e32 v13, v2
	v_lshl_add_u64 v[14:15], s[14:15], 0, v[12:13]
	s_movk_i32 s0, 0x1000
	v_add_co_u32_e64 v16, s[0:1], s0, v14
	v_mov_b32_e32 v49, v2
	s_nop 0
	v_addc_co_u32_e64 v17, s[0:1], 0, v15, s[0:1]
	s_movk_i32 s0, 0x2000
	s_nop 0
	v_add_co_u32_e64 v18, s[0:1], s0, v14
	v_lshl_add_u64 v[4:5], s[18:19], 0, v[48:49]
	s_nop 0
	v_addc_co_u32_e64 v19, s[0:1], 0, v15, s[0:1]
	v_lshl_add_u64 v[4:5], v[4:5], 0, s[8:9]
	s_movk_i32 s0, 0x3000
	v_lshl_add_u64 v[6:7], v[20:21], 1, v[4:5]
	v_lshl_add_u64 v[4:5], v[22:23], 1, v[4:5]
	v_add_co_u32_e64 v14, s[0:1], s0, v14
	global_load_dwordx4 v[8:11], v[6:7], off offset:1024
	s_nop 0
	v_addc_co_u32_e64 v15, s[0:1], 0, v15, s[0:1]
	global_load_dwordx4 v[4:7], v[4:5], off offset:1024
	s_nop 0
	global_load_dword v51, v12, s[14:15]
	global_load_dword v91, v12, s[14:15] offset:1024
	global_load_dword v73, v12, s[14:15] offset:2048
	global_load_dword v77, v12, s[14:15] offset:3072
	global_load_dword v75, v[18:19], off offset:-4096
	global_load_dword v79, v[16:17], off offset:1024
	global_load_dword v69, v[16:17], off offset:2048
	global_load_dword v71, v[16:17], off offset:3072
	global_load_dword v92, v[18:19], off
	global_load_dword v93, v[18:19], off offset:1024
	global_load_dword v72, v[18:19], off offset:2048
	global_load_dword v76, v[18:19], off offset:3072
	v_lshl_add_u64 v[16:17], s[18:19], 0, v[24:25]
	global_load_dword v74, v[14:15], off
	global_load_dword v78, v[14:15], off offset:1024
	global_load_dword v68, v[14:15], off offset:2048
	global_load_dword v70, v[14:15], off offset:3072
	global_load_dword v94, v12, s[16:17]
	s_nop 0
	global_load_dwordx4 v[12:15], v[16:17], off offset:3920
	s_nop 0
	global_load_dwordx4 v[16:19], v[16:17], off offset:3904
	v_lshl_add_u64 v[184:185], s[18:19], 0, v[26:27]
	global_load_dwordx4 v[120:123], v[184:185], off offset:3920
	global_load_dwordx4 v[124:127], v[184:185], off offset:3904
	v_lshl_add_u64 v[184:185], s[18:19], 0, v[28:29]
	global_load_dwordx4 v[128:131], v[184:185], off offset:3920
	global_load_dwordx4 v[132:135], v[184:185], off offset:3904
	v_lshl_add_u64 v[184:185], s[18:19], 0, v[30:31]
	global_load_dwordx4 v[136:139], v[184:185], off offset:3920
	global_load_dwordx4 v[140:143], v[184:185], off offset:3904
	v_lshl_add_u64 v[184:185], s[18:19], 0, v[32:33]
	global_load_dwordx4 v[144:147], v[184:185], off offset:3920
	global_load_dwordx4 v[148:151], v[184:185], off offset:3904
	v_lshl_add_u64 v[184:185], s[18:19], 0, v[34:35]
	global_load_dwordx4 v[152:155], v[184:185], off offset:3920
	global_load_dwordx4 v[156:159], v[184:185], off offset:3904
	v_lshl_add_u64 v[184:185], s[18:19], 0, v[36:37]
	global_load_dwordx4 v[160:163], v[184:185], off offset:3920
	global_load_dwordx4 v[164:167], v[184:185], off offset:3904
	v_lshl_add_u64 v[184:185], s[18:19], 0, v[38:39]
	global_load_dwordx4 v[176:179], v[184:185], off offset:3920
	global_load_dwordx4 v[180:183], v[184:185], off offset:3904
	s_mov_b32 s0, 0xbfb8aa3b
	s_mov_b32 s1, 0xbd800000
	s_ashr_i32 s5, s4, 31
	global_load_ushort v186, v[66:67], off offset:512
	global_load_ushort v187, v[64:65], off offset:512
	global_load_ushort v188, v[62:63], off offset:512
	global_load_ushort v189, v[60:61], off offset:512
	global_load_ushort v190, v[58:59], off offset:512
	global_load_ushort v191, v[56:57], off offset:512
	global_load_ushort v192, v[54:55], off offset:512
	global_load_ushort v193, v[52:53], off offset:512
	s_waitcnt vmcnt(0)
	v_lshlrev_b32_e32 v49, 16, v16
	v_and_b32_e32 v16, 0xffff0000, v16
	v_mul_f32_e32 v16, v91, v16
	v_fmac_f32_e32 v16, v51, v49
	v_lshlrev_b32_e32 v49, 16, v12
	v_and_b32_e32 v12, 0xffff0000, v12
	v_mul_f32_e32 v12, v93, v12
	v_add_f32_e32 v16, v94, v16
	v_fmac_f32_e32 v12, v92, v49
	v_add_f32_e32 v12, v12, v16
	v_lshlrev_b32_e32 v16, 16, v17
	v_and_b32_e32 v17, 0xffff0000, v17
	v_mul_f32_e32 v17, v77, v17
	v_fmac_f32_e32 v17, v73, v16
	v_lshlrev_b32_e32 v16, 16, v13
	v_and_b32_e32 v13, 0xffff0000, v13
	v_mul_f32_e32 v13, v76, v13
	v_add_f32_e32 v12, v17, v12
	v_fmac_f32_e32 v13, v72, v16
	v_and_b32_e32 v16, 0xffff0000, v18
	v_add_f32_e32 v12, v13, v12
	v_lshlrev_b32_e32 v13, 16, v18
	v_mul_f32_e32 v16, v79, v16
	v_fmac_f32_e32 v16, v75, v13
	v_lshlrev_b32_e32 v13, 16, v14
	v_and_b32_e32 v14, 0xffff0000, v14
	v_mul_f32_e32 v14, v78, v14
	v_add_f32_e32 v12, v16, v12
	v_fmac_f32_e32 v14, v74, v13
	v_and_b32_e32 v17, 0xffff0000, v19
	v_and_b32_e32 v16, 0xffff0000, v15
	v_add_f32_e32 v18, v14, v12
	v_lshlrev_b32_e32 v13, 16, v19
	v_lshlrev_b32_e32 v12, 16, v15
	v_pk_mul_f32 v[14:15], v[70:71], v[16:17]
	v_lshl_add_u64 v[16:17], s[18:19], 0, v[26:27]
	v_pk_fma_f32 v[12:13], v[68:69], v[12:13], v[14:15]
	s_nop 0
	v_add_f32_e32 v13, v13, v18
	v_add_f32_e32 v12, v12, v13
	v_max_f32_e64 v13, -v12, 0
	v_mul_f32_e64 v12, |v12|, s0
	v_exp_f32_e32 v12, v12
	s_nop 0
	v_add_f32_e32 v12, 1.0, v12
	v_log_f32_e32 v12, v12
	s_nop 0
	v_fmac_f32_e32 v13, 0x3f317218, v12
	v_fma_f32 v49, v13, s1, 0
	v_mov_b32_e32 v12, v120
	v_mov_b32_e32 v13, v121
	v_mov_b32_e32 v14, v122
	v_mov_b32_e32 v15, v123
	s_nop 0
	v_mov_b32_e32 v16, v124
	v_mov_b32_e32 v17, v125
	v_mov_b32_e32 v18, v126
	v_mov_b32_e32 v19, v127
	s_waitcnt vmcnt(0)
; DI float fexp(float x) { return __builtin_amdgcn_exp2f(x * LOG2E); }
; DI void gla_gates(const bf16_t* Urow0, const float* wg, const float* bg, int h, LAS float* tot, float (&bc)[8], float& total, int tid) {
;     ...
;     for (int tt = 0; tt < 8; ++tt) { const bf16_t* gl = Urow0 + (size_t)(8 * seg + tt) * OD_INP + 1952;
;         const u32x4 a0 = *(const u32x4*)gl, a1 = *(const u32x4*)(gl + 8); float z = bias;
; #pragma unroll
;         for (int p = 0; p < 4; ++p) { z += bflo(a0[p]) * wr[2 * p] + bfhi(a0[p]) * wr[2 * p + 1]; z += bflo(a1[p]) * wr[8 + 2 * p] + bfhi(a1[p]) * wr[9 + 2 * p]; }
;         const float ls = -(fmaxf(-z, 0.f) + __builtin_amdgcn_logf(1.f + fexp(-fabsf(z))) * 0.6931471805599453f);
;         run += ls * (1.f / 16.f); bc[tt] = run; }
	v_lshlrev_b32_e32 v95, 16, v16
	v_and_b32_e32 v16, 0xffff0000, v16
	v_mul_f32_e32 v16, v91, v16
	v_fmac_f32_e32 v16, v51, v95
	v_lshlrev_b32_e32 v95, 16, v12
	v_and_b32_e32 v12, 0xffff0000, v12
	v_mul_f32_e32 v12, v93, v12
	v_add_f32_e32 v16, v94, v16
	v_fmac_f32_e32 v12, v92, v95
	v_add_f32_e32 v12, v12, v16
	v_lshlrev_b32_e32 v16, 16, v17
	v_and_b32_e32 v17, 0xffff0000, v17
	v_mul_f32_e32 v17, v77, v17
	v_fmac_f32_e32 v17, v73, v16
	v_lshlrev_b32_e32 v16, 16, v13
	v_and_b32_e32 v13, 0xffff0000, v13
	v_mul_f32_e32 v13, v76, v13
	v_add_f32_e32 v12, v17, v12
	v_fmac_f32_e32 v13, v72, v16
	v_and_b32_e32 v16, 0xffff0000, v18
	v_add_f32_e32 v12, v13, v12
	v_lshlrev_b32_e32 v13, 16, v18
	v_mul_f32_e32 v16, v79, v16
	v_fmac_f32_e32 v16, v75, v13
	v_lshlrev_b32_e32 v13, 16, v14
	v_and_b32_e32 v14, 0xffff0000, v14
	v_mul_f32_e32 v14, v78, v14
	v_add_f32_e32 v12, v16, v12
	v_fmac_f32_e32 v14, v74, v13
	v_and_b32_e32 v17, 0xffff0000, v19
	v_and_b32_e32 v16, 0xffff0000, v15
	v_add_f32_e32 v18, v14, v12
	v_lshlrev_b32_e32 v13, 16, v19
	v_lshlrev_b32_e32 v12, 16, v15
	v_pk_mul_f32 v[14:15], v[70:71], v[16:17]
	v_lshl_add_u64 v[16:17], s[18:19], 0, v[28:29]
	v_pk_fma_f32 v[12:13], v[68:69], v[12:13], v[14:15]
	s_nop 0
	v_add_f32_e32 v13, v13, v18
	v_add_f32_e32 v12, v12, v13
	v_max_f32_e64 v13, -v12, 0
	v_mul_f32_e64 v12, |v12|, s0
	v_exp_f32_e32 v12, v12
	s_nop 0
	v_add_f32_e32 v12, 1.0, v12
	v_log_f32_e32 v12, v12
	s_nop 0
	v_fmac_f32_e32 v13, 0x3f317218, v12
	v_fmamk_f32 v95, v13, 0xbd800000, v49
	v_mov_b32_e32 v12, v128
	v_mov_b32_e32 v13, v129
	v_mov_b32_e32 v14, v130
	v_mov_b32_e32 v15, v131
	s_nop 0
	v_mov_b32_e32 v16, v132
	v_mov_b32_e32 v17, v133
	v_mov_b32_e32 v18, v134
	v_mov_b32_e32 v19, v135
	s_waitcnt vmcnt(0)
	v_lshlrev_b32_e32 v96, 16, v16
	v_and_b32_e32 v16, 0xffff0000, v16
	v_mul_f32_e32 v16, v91, v16
	v_fmac_f32_e32 v16, v51, v96
	v_lshlrev_b32_e32 v96, 16, v12
	v_and_b32_e32 v12, 0xffff0000, v12
	v_mul_f32_e32 v12, v93, v12
	v_add_f32_e32 v16, v94, v16
	v_fmac_f32_e32 v12, v92, v96
	v_add_f32_e32 v12, v12, v16
	v_lshlrev_b32_e32 v16, 16, v17
	v_and_b32_e32 v17, 0xffff0000, v17
	v_mul_f32_e32 v17, v77, v17
	v_fmac_f32_e32 v17, v73, v16
	v_lshlrev_b32_e32 v16, 16, v13
	v_and_b32_e32 v13, 0xffff0000, v13
	v_mul_f32_e32 v13, v76, v13
	v_add_f32_e32 v12, v17, v12
	v_fmac_f32_e32 v13, v72, v16
	v_and_b32_e32 v16, 0xffff0000, v18
	v_add_f32_e32 v12, v13, v12
	v_lshlrev_b32_e32 v13, 16, v18
	v_mul_f32_e32 v16, v79, v16
	v_fmac_f32_e32 v16, v75, v13
	v_lshlrev_b32_e32 v13, 16, v14
	v_and_b32_e32 v14, 0xffff0000, v14
	v_mul_f32_e32 v14, v78, v14
	v_add_f32_e32 v12, v16, v12
	v_fmac_f32_e32 v14, v74, v13
	v_and_b32_e32 v17, 0xffff0000, v19
	v_and_b32_e32 v16, 0xffff0000, v15
	v_add_f32_e32 v18, v14, v12
	v_lshlrev_b32_e32 v13, 16, v19
	v_lshlrev_b32_e32 v12, 16, v15
	v_pk_mul_f32 v[14:15], v[70:71], v[16:17]
	v_lshl_add_u64 v[16:17], s[18:19], 0, v[30:31]
	v_pk_fma_f32 v[12:13], v[68:69], v[12:13], v[14:15]
	s_nop 0
	v_add_f32_e32 v13, v13, v18
	v_add_f32_e32 v12, v12, v13
	v_max_f32_e64 v13, -v12, 0
	v_mul_f32_e64 v12, |v12|, s0
	v_exp_f32_e32 v12, v12
	s_nop 0
	v_add_f32_e32 v12, 1.0, v12
	v_log_f32_e32 v12, v12
	s_nop 0
	v_fmac_f32_e32 v13, 0x3f317218, v12
	v_fmamk_f32 v96, v13, 0xbd800000, v95
	v_mov_b32_e32 v12, v136
	v_mov_b32_e32 v13, v137
	v_mov_b32_e32 v14, v138
	v_mov_b32_e32 v15, v139
	s_nop 0
	v_mov_b32_e32 v16, v140
	v_mov_b32_e32 v17, v141
	v_mov_b32_e32 v18, v142
	v_mov_b32_e32 v19, v143
	s_waitcnt vmcnt(0)
	v_lshlrev_b32_e32 v97, 16, v16
	v_and_b32_e32 v16, 0xffff0000, v16
	v_mul_f32_e32 v16, v91, v16
	v_fmac_f32_e32 v16, v51, v97
	v_lshlrev_b32_e32 v97, 16, v12
	v_and_b32_e32 v12, 0xffff0000, v12
	v_mul_f32_e32 v12, v93, v12
	v_add_f32_e32 v16, v94, v16
	v_fmac_f32_e32 v12, v92, v97
	v_add_f32_e32 v12, v12, v16
	v_lshlrev_b32_e32 v16, 16, v17
	v_and_b32_e32 v17, 0xffff0000, v17
	v_mul_f32_e32 v17, v77, v17
	v_fmac_f32_e32 v17, v73, v16
	v_lshlrev_b32_e32 v16, 16, v13
	v_and_b32_e32 v13, 0xffff0000, v13
	v_mul_f32_e32 v13, v76, v13
	v_add_f32_e32 v12, v17, v12
	v_fmac_f32_e32 v13, v72, v16
	v_and_b32_e32 v16, 0xffff0000, v18
	v_add_f32_e32 v12, v13, v12
	v_lshlrev_b32_e32 v13, 16, v18
	v_mul_f32_e32 v16, v79, v16
	v_fmac_f32_e32 v16, v75, v13
	v_lshlrev_b32_e32 v13, 16, v14
	v_and_b32_e32 v14, 0xffff0000, v14
	v_mul_f32_e32 v14, v78, v14
	v_add_f32_e32 v12, v16, v12
	v_fmac_f32_e32 v14, v74, v13
	v_and_b32_e32 v17, 0xffff0000, v19
	v_and_b32_e32 v16, 0xffff0000, v15
	v_add_f32_e32 v18, v14, v12
	v_lshlrev_b32_e32 v13, 16, v19
	v_lshlrev_b32_e32 v12, 16, v15
	v_pk_mul_f32 v[14:15], v[70:71], v[16:17]
	v_lshl_add_u64 v[16:17], s[18:19], 0, v[32:33]
	v_pk_fma_f32 v[12:13], v[68:69], v[12:13], v[14:15]
	s_nop 0
	v_add_f32_e32 v13, v13, v18
	v_add_f32_e32 v12, v12, v13
	v_max_f32_e64 v13, -v12, 0
	v_mul_f32_e64 v12, |v12|, s0
	v_exp_f32_e32 v12, v12
	s_nop 0
	v_add_f32_e32 v12, 1.0, v12
	v_log_f32_e32 v12, v12
	s_nop 0
	v_fmac_f32_e32 v13, 0x3f317218, v12
	v_fmamk_f32 v97, v13, 0xbd800000, v96
	v_mov_b32_e32 v12, v144
	v_mov_b32_e32 v13, v145
	v_mov_b32_e32 v14, v146
	v_mov_b32_e32 v15, v147
	s_nop 0
	v_mov_b32_e32 v16, v148
	v_mov_b32_e32 v17, v149
	v_mov_b32_e32 v18, v150
	v_mov_b32_e32 v19, v151
	s_waitcnt vmcnt(0)
; DI float fexp(float x) { return __builtin_amdgcn_exp2f(x * LOG2E); }
; DI void gla_gates(const bf16_t* Urow0, const float* wg, const float* bg, int h, LAS float* tot, float (&bc)[8], float& total, int tid) {
;     ...
;     for (int tt = 0; tt < 8; ++tt) { const bf16_t* gl = Urow0 + (size_t)(8 * seg + tt) * OD_INP + 1952;
;         const u32x4 a0 = *(const u32x4*)gl, a1 = *(const u32x4*)(gl + 8); float z = bias;
; #pragma unroll
;         for (int p = 0; p < 4; ++p) { z += bflo(a0[p]) * wr[2 * p] + bfhi(a0[p]) * wr[2 * p + 1]; z += bflo(a1[p]) * wr[8 + 2 * p] + bfhi(a1[p]) * wr[9 + 2 * p]; }
;         const float ls = -(fmaxf(-z, 0.f) + __builtin_amdgcn_logf(1.f + fexp(-fabsf(z))) * 0.6931471805599453f);
;         run += ls * (1.f / 16.f); bc[tt] = run; }
;     tot[seg * 64 + d] = run; __syncthreads();
; DI void gla_local_phase(LAS unsigned char* lds, const bf16_t* U, const float* wg, const float* bg, float* GST, float* DVEC) {
;     ...
;         for (int tt = 0; tt < 8; ++tt) kraw[tt] = Urow0[(size_t)(8 * seg + tt) * OD_INP + 256 + h * 64 + d];
	v_lshlrev_b32_e32 v98, 16, v16
	v_and_b32_e32 v16, 0xffff0000, v16
	v_mul_f32_e32 v16, v91, v16
	v_fmac_f32_e32 v16, v51, v98
	v_lshlrev_b32_e32 v98, 16, v12
	v_and_b32_e32 v12, 0xffff0000, v12
	v_mul_f32_e32 v12, v93, v12
	v_add_f32_e32 v16, v94, v16
	v_fmac_f32_e32 v12, v92, v98
	v_add_f32_e32 v12, v12, v16
	v_lshlrev_b32_e32 v16, 16, v17
	v_and_b32_e32 v17, 0xffff0000, v17
	v_mul_f32_e32 v17, v77, v17
	v_fmac_f32_e32 v17, v73, v16
	v_lshlrev_b32_e32 v16, 16, v13
	v_and_b32_e32 v13, 0xffff0000, v13
	v_mul_f32_e32 v13, v76, v13
	v_add_f32_e32 v12, v17, v12
	v_fmac_f32_e32 v13, v72, v16
	v_and_b32_e32 v17, 0xffff0000, v18
	v_and_b32_e32 v16, 0xffff0000, v14
	v_add_f32_e32 v98, v13, v12
	v_lshlrev_b32_e32 v13, 16, v18
	v_lshlrev_b32_e32 v12, 16, v14
	v_pk_mul_f32 v[16:17], v[78:79], v[16:17]
	s_nop 0
	v_pk_fma_f32 v[12:13], v[74:75], v[12:13], v[16:17]
	v_and_b32_e32 v17, 0xffff0000, v19
	v_add_f32_e32 v13, v13, v98
	v_and_b32_e32 v16, 0xffff0000, v15
	v_add_f32_e32 v18, v12, v13
	v_lshlrev_b32_e32 v13, 16, v19
	v_lshlrev_b32_e32 v12, 16, v15
	v_pk_mul_f32 v[14:15], v[70:71], v[16:17]
	v_lshl_add_u64 v[16:17], s[18:19], 0, v[34:35]
	v_pk_fma_f32 v[12:13], v[68:69], v[12:13], v[14:15]
	s_nop 0
	v_add_f32_e32 v13, v13, v18
	v_add_f32_e32 v12, v12, v13
	v_max_f32_e64 v13, -v12, 0
	v_mul_f32_e64 v12, |v12|, s0
	v_exp_f32_e32 v12, v12
	s_nop 0
	v_add_f32_e32 v12, 1.0, v12
	v_log_f32_e32 v12, v12
	s_nop 0
	v_fmac_f32_e32 v13, 0x3f317218, v12
	v_fmamk_f32 v98, v13, 0xbd800000, v97
	v_mov_b32_e32 v12, v152
	v_mov_b32_e32 v13, v153
	v_mov_b32_e32 v14, v154
	v_mov_b32_e32 v15, v155
	s_nop 0
	v_mov_b32_e32 v16, v156
	v_mov_b32_e32 v17, v157
	v_mov_b32_e32 v18, v158
	v_mov_b32_e32 v19, v159
	s_waitcnt vmcnt(0)
	v_lshlrev_b32_e32 v99, 16, v16
	v_and_b32_e32 v16, 0xffff0000, v16
	v_mul_f32_e32 v16, v91, v16
	v_fmac_f32_e32 v16, v51, v99
	v_lshlrev_b32_e32 v99, 16, v12
	v_and_b32_e32 v12, 0xffff0000, v12
	v_mul_f32_e32 v12, v93, v12
	v_add_f32_e32 v16, v94, v16
	v_fmac_f32_e32 v12, v92, v99
	v_add_f32_e32 v12, v12, v16
	v_lshlrev_b32_e32 v16, 16, v17
	v_and_b32_e32 v17, 0xffff0000, v17
	v_mul_f32_e32 v17, v77, v17
	v_fmac_f32_e32 v17, v73, v16
	v_lshlrev_b32_e32 v16, 16, v13
	v_and_b32_e32 v13, 0xffff0000, v13
	v_mul_f32_e32 v13, v76, v13
	v_add_f32_e32 v12, v17, v12
	v_fmac_f32_e32 v13, v72, v16
	v_and_b32_e32 v17, 0xffff0000, v18
	v_and_b32_e32 v16, 0xffff0000, v14
	v_add_f32_e32 v99, v13, v12
	v_lshlrev_b32_e32 v13, 16, v18
	v_lshlrev_b32_e32 v12, 16, v14
	v_pk_mul_f32 v[16:17], v[78:79], v[16:17]
	s_nop 0
	v_pk_fma_f32 v[12:13], v[74:75], v[12:13], v[16:17]
	v_and_b32_e32 v17, 0xffff0000, v19
	v_add_f32_e32 v13, v13, v99
	v_and_b32_e32 v16, 0xffff0000, v15
	v_add_f32_e32 v18, v12, v13
	v_lshlrev_b32_e32 v13, 16, v19
	v_lshlrev_b32_e32 v12, 16, v15
	v_pk_mul_f32 v[14:15], v[70:71], v[16:17]
	v_lshl_add_u64 v[16:17], s[18:19], 0, v[36:37]
	v_pk_fma_f32 v[12:13], v[68:69], v[12:13], v[14:15]
	s_nop 0
	v_add_f32_e32 v13, v13, v18
	v_add_f32_e32 v12, v12, v13
	v_max_f32_e64 v13, -v12, 0
	v_mul_f32_e64 v12, |v12|, s0
	v_exp_f32_e32 v12, v12
	s_nop 0
	v_add_f32_e32 v12, 1.0, v12
	v_log_f32_e32 v12, v12
	s_nop 0
	v_fmac_f32_e32 v13, 0x3f317218, v12
	v_fmamk_f32 v99, v13, 0xbd800000, v98
	v_mov_b32_e32 v12, v160
	v_mov_b32_e32 v13, v161
	v_mov_b32_e32 v14, v162
	v_mov_b32_e32 v15, v163
	s_nop 0
	v_mov_b32_e32 v16, v164
	v_mov_b32_e32 v17, v165
	v_mov_b32_e32 v18, v166
	v_mov_b32_e32 v19, v167
	s_waitcnt vmcnt(0)
	v_lshlrev_b32_e32 v100, 16, v16
	v_and_b32_e32 v16, 0xffff0000, v16
	v_mul_f32_e32 v16, v91, v16
	v_fmac_f32_e32 v16, v51, v100
	v_lshlrev_b32_e32 v100, 16, v12
	v_and_b32_e32 v12, 0xffff0000, v12
	v_mul_f32_e32 v12, v93, v12
	v_add_f32_e32 v16, v94, v16
	v_fmac_f32_e32 v12, v92, v100
	v_add_f32_e32 v102, v12, v16
	v_lshlrev_b32_e32 v101, 16, v17
	v_and_b32_e32 v17, 0xffff0000, v17
	v_and_b32_e32 v16, 0xffff0000, v13
	v_lshlrev_b32_e32 v100, 16, v13
	v_pk_mul_f32 v[12:13], v[76:77], v[16:17]
	v_and_b32_e32 v17, 0xffff0000, v18
	v_pk_fma_f32 v[12:13], v[72:73], v[100:101], v[12:13]
	v_and_b32_e32 v16, 0xffff0000, v14
	v_add_f32_e32 v13, v13, v102
	v_add_f32_e32 v100, v12, v13
	v_lshlrev_b32_e32 v13, 16, v18
	v_lshlrev_b32_e32 v12, 16, v14
	v_pk_mul_f32 v[16:17], v[78:79], v[16:17]
	s_nop 0
	v_pk_fma_f32 v[12:13], v[74:75], v[12:13], v[16:17]
	v_and_b32_e32 v17, 0xffff0000, v19
	v_add_f32_e32 v13, v13, v100
	v_and_b32_e32 v16, 0xffff0000, v15
	v_add_f32_e32 v18, v12, v13
	v_lshlrev_b32_e32 v13, 16, v19
	v_lshlrev_b32_e32 v12, 16, v15
	v_pk_mul_f32 v[14:15], v[70:71], v[16:17]
	v_lshl_add_u64 v[16:17], s[18:19], 0, v[38:39]
	v_pk_fma_f32 v[12:13], v[68:69], v[12:13], v[14:15]
	s_nop 0
	v_add_f32_e32 v13, v13, v18
	v_add_f32_e32 v12, v12, v13
	v_max_f32_e64 v13, -v12, 0
	v_mul_f32_e64 v12, |v12|, s0
	v_exp_f32_e32 v12, v12
	s_nop 0
	v_add_f32_e32 v12, 1.0, v12
	v_log_f32_e32 v12, v12
	s_nop 0
	v_fmac_f32_e32 v13, 0x3f317218, v12
	v_fmamk_f32 v100, v13, 0xbd800000, v99
	v_mov_b32_e32 v12, v176
	v_mov_b32_e32 v13, v177
	v_mov_b32_e32 v14, v178
	v_mov_b32_e32 v15, v179
	s_nop 0
	v_mov_b32_e32 v16, v180
	v_mov_b32_e32 v17, v181
	v_mov_b32_e32 v18, v182
	v_mov_b32_e32 v19, v183
	s_waitcnt vmcnt(0)
	v_lshlrev_b32_e32 v101, 16, v16
	v_and_b32_e32 v16, 0xffff0000, v16
	v_mul_f32_e32 v16, v91, v16
	v_fmac_f32_e32 v16, v51, v101
	v_lshlrev_b32_e32 v51, 16, v12
	v_and_b32_e32 v12, 0xffff0000, v12
	v_mul_f32_e32 v12, v93, v12
	v_add_f32_e32 v16, v94, v16
	v_fmac_f32_e32 v12, v92, v51
	v_add_f32_e32 v51, v12, v16
	v_lshlrev_b32_e32 v93, 16, v17
	v_and_b32_e32 v17, 0xffff0000, v17
	v_and_b32_e32 v16, 0xffff0000, v13
	v_lshlrev_b32_e32 v92, 16, v13
	v_pk_mul_f32 v[12:13], v[76:77], v[16:17]
	v_and_b32_e32 v17, 0xffff0000, v18
	v_pk_fma_f32 v[12:13], v[72:73], v[92:93], v[12:13]
	v_and_b32_e32 v16, 0xffff0000, v14
	v_add_f32_e32 v13, v13, v51
	v_add_f32_e32 v51, v12, v13
	v_lshlrev_b32_e32 v13, 16, v18
	v_lshlrev_b32_e32 v12, 16, v14
	v_pk_mul_f32 v[16:17], v[78:79], v[16:17]
	s_nop 0
	v_pk_fma_f32 v[12:13], v[74:75], v[12:13], v[16:17]
	v_and_b32_e32 v17, 0xffff0000, v19
	v_add_f32_e32 v13, v13, v51
	v_and_b32_e32 v16, 0xffff0000, v15
	v_add_f32_e32 v18, v12, v13
	v_lshlrev_b32_e32 v13, 16, v19
	v_lshlrev_b32_e32 v12, 16, v15
	v_pk_mul_f32 v[14:15], v[70:71], v[16:17]
	s_nop 0
	v_pk_fma_f32 v[12:13], v[68:69], v[12:13], v[14:15]
	s_nop 0
	v_add_f32_e32 v13, v13, v18
	v_mov_b32_e32 v18, v186
	v_mov_b32_e32 v19, v187
	v_mov_b32_e32 v51, v188
	s_nop 0
	v_mov_b32_e32 v60, v189
	s_nop 0
	v_mov_b32_e32 v58, v190
	s_nop 0
	v_mov_b32_e32 v56, v191
	s_nop 0
	v_mov_b32_e32 v54, v192
	s_nop 0
	v_mov_b32_e32 v55, v193
	v_add_f32_e32 v12, v12, v13
	v_max_f32_e64 v13, -v12, 0
	v_mul_f32_e64 v12, |v12|, s0
	v_exp_f32_e32 v12, v12
	s_waitcnt vmcnt(1)
	v_lshlrev_b32_e32 v54, 16, v54
	v_add_f32_e32 v12, 1.0, v12
	v_log_f32_e32 v12, v12
	s_waitcnt vmcnt(0)
	v_lshlrev_b32_e32 v55, 16, v55
	v_fmac_f32_e32 v13, 0x3f317218, v12
	v_fmamk_f32 v13, v13, 0xbd800000, v100
	ds_write_b32 v1, v13
	s_waitcnt lgkmcnt(0)
	s_barrier
; #define LAS __attribute__((address_space(3)))
; __device__ __forceinline__ int opq_tid() { int t = threadIdx.x; asm volatile("" : "+v"(t)); return t; }
; DI void gla_gates(const bf16_t* Urow0, const float* wg, const float* bg, int h, LAS float* tot, float (&bc)[8], float& total, int tid) {
;     ...
;     float prefix = 0.f; total = 0.f;
; #pragma unroll
;     for (int s = 0; s < 8; ++s) { const float v = tot[s * 64 + d]; total += v; if (s < seg) prefix += v; }
; #pragma unroll
;     for (int tt = 0; tt < 8; ++tt) bc[tt] += prefix;
; }
; DI void gla_vt_load(u32x4 (&vv)[2], const bf16_t* Urow0, int h, int tid) {
; #pragma unroll
;     for (int i = 0; i < 2; ++i) { const int id = tid + 512 * i, t = id & 63, c8 = id >> 6; vv[i] = *(const u32x4*)(Urow0 + (size_t)t * OD_INP + 512 + h * 128 + 8 * c8); }
; }
; DI void gla_vt_store(LAS bf16_t* Vt, const u32x4 (&vv)[2], int tid) {
; #pragma unroll
;     for (int i = 0; i < 2; ++i) { const int id = tid + 512 * i, t = id & 63, c8 = id >> 6;
; #pragma unroll
;         for (int e = 0; e < 8; ++e) Vt[(8 * c8 + e) * 72 + t] = (bf16_t)(vv[i][e >> 1] >> (16 * (e & 1))); }
; }
; DI void gla_local_phase(LAS unsigned char* lds, const bf16_t* U, const float* wg, const float* bg, float* GST, float* DVEC) {
;     const int tid = opq_tid(), lane = tid & 63, w = tid >> 6, l16 = lane & 15, g = lane >> 4, d = tid & 63, seg = tid >> 6;
;     LAS float* tot = (LAS float*)lds; LAS bf16_t* Kt = (LAS bf16_t*)(lds + 2048); LAS bf16_t* Vt = (LAS bf16_t*)(lds + 2048 + 9216);
;     for (int unit = opq_bid(); unit < 2048; unit += gridDim.x) {
;         const int c = unit & 255, bh = unit >> 8, b = bh >> 2, h = bh & 3;
;         const bf16_t* Urow0 = U + ((size_t)b * SEQ + (size_t)c * 64) * OD_INP;
;         u32x4 vv[2]; gla_vt_load(vv, Urow0, h, tid);
;         bf16_t kraw[8];
; #pragma unroll
;         for (int tt = 0; tt < 8; ++tt) kraw[tt] = Urow0[(size_t)(8 * seg + tt) * OD_INP + 256 + h * 64 + d];
;         float bc[8], total; gla_gates(Urow0, wg, bg, h, tot, bc, total, tid);
;         float kd[8];
; #pragma unroll
;         for (int tt = 0; tt < 8; ++tt) kd[tt] = bf2f(kraw[tt]) * fexp(total - bc[tt]);
;         u32x4 pk; pk.x = pk2(kd[0], kd[1]); pk.y = pk2(kd[2], kd[3]); pk.z = pk2(kd[4], kd[5]); pk.w = pk2(kd[6], kd[7]);
;         *(LAS u32x4*)(Kt + d * 72 + 8 * seg) = pk;
;         if (seg == 0) DVEC[(size_t)unit * 64 + d] = fexp(total);
	ds_read2st64_b32 v[14:15], v3 offset1:1
	s_waitcnt lgkmcnt(0)
	v_add_f32_e32 v12, 0, v14
	v_cndmask_b32_e32 v14, 0, v12, vcc
	v_add_f32_e32 v12, v15, v12
	v_add_f32_e32 v15, v15, v14
	v_cndmask_b32_e64 v16, v14, v15, s[38:39]
	ds_read2st64_b32 v[14:15], v3 offset0:2 offset1:3
	s_waitcnt lgkmcnt(0)
	v_add_f32_e32 v12, v14, v12
	v_add_f32_e32 v14, v14, v16
	v_cndmask_b32_e64 v14, v16, v14, s[40:41]
	v_add_f32_e32 v12, v15, v12
	v_add_f32_e32 v15, v15, v14
	v_cndmask_b32_e64 v16, v14, v15, s[42:43]
	ds_read2st64_b32 v[14:15], v3 offset0:4 offset1:5
	s_waitcnt lgkmcnt(0)
	v_add_f32_e32 v12, v14, v12
	v_add_f32_e32 v14, v14, v16
	v_cndmask_b32_e64 v14, v16, v14, s[44:45]
	v_add_f32_e32 v12, v15, v12
	v_add_f32_e32 v15, v15, v14
	v_cndmask_b32_e64 v16, v14, v15, s[46:47]
	ds_read2st64_b32 v[14:15], v3 offset0:6 offset1:7
	s_waitcnt lgkmcnt(0)
	v_add_f32_e32 v12, v14, v12
	v_add_f32_e32 v14, v14, v16
	v_cndmask_b32_e64 v14, v16, v14, s[48:49]
	v_add_f32_e32 v16, v15, v14
	v_cndmask_b32_e64 v17, v14, v16, s[50:51]
	v_mov_b32_e32 v16, v15
	v_add_f32_e32 v14, v49, v17
	v_add_f32_e32 v49, v95, v17
	v_pk_add_f32 v[12:13], v[16:17], v[12:13]
	v_add_f32_e32 v52, v96, v17
	v_sub_f32_e32 v14, v12, v14
	v_sub_f32_e32 v15, v12, v49
	v_mul_f32_e32 v14, 0x3fb8aa3b, v14
	v_mul_f32_e32 v15, 0x3fb8aa3b, v15
	v_exp_f32_e32 v14, v14
	v_exp_f32_e32 v15, v15
	v_add_f32_e32 v53, v97, v17
	v_add_f32_e32 v57, v98, v17
	v_add_f32_e32 v59, v99, v17
	v_add_f32_e32 v61, v100, v17
	v_lshlrev_b32_e32 v17, 16, v19
	v_lshlrev_b32_e32 v16, 16, v18
	v_pk_mul_f32 v[14:15], v[14:15], v[16:17]
	v_sub_f32_e32 v16, v12, v52
	v_sub_f32_e32 v17, v12, v53
	v_mul_f32_e32 v16, 0x3fb8aa3b, v16
	v_mul_f32_e32 v17, 0x3fb8aa3b, v17
	v_exp_f32_e32 v16, v16
	v_exp_f32_e32 v17, v17
	v_lshlrev_b32_e32 v19, 16, v60
	v_lshlrev_b32_e32 v18, 16, v51
	v_sub_f32_e32 v49, v12, v61
	v_pk_mul_f32 v[16:17], v[16:17], v[18:19]
	v_sub_f32_e32 v18, v12, v57
	v_sub_f32_e32 v19, v12, v59
	v_mul_f32_e32 v18, 0x3fb8aa3b, v18
	v_mul_f32_e32 v19, 0x3fb8aa3b, v19
	v_exp_f32_e32 v18, v18
	v_exp_f32_e32 v19, v19
	v_sub_f32_e32 v13, v12, v13
	v_lshlrev_b32_e32 v53, 16, v56
	v_lshlrev_b32_e32 v52, 16, v58
	v_mul_f32_e32 v49, 0x3fb8aa3b, v49
	v_mul_f32_e32 v13, 0x3fb8aa3b, v13
	v_pk_mul_f32 v[18:19], v[18:19], v[52:53]
	v_exp_f32_e32 v52, v49
	v_exp_f32_e32 v53, v13
	v_cvt_pk_bf16_f32 v14, v14, v15
	v_cvt_pk_bf16_f32 v15, v16, v17
	v_cvt_pk_bf16_f32 v16, v18, v19
	v_pk_mul_f32 v[52:53], v[52:53], v[54:55]
	v_add_u32_e32 v13, v80, v81
	v_cvt_pk_bf16_f32 v17, v52, v53
	ds_write_b128 v13, v[14:17] offset:2048
	s_and_saveexec_b64 s[0:1], s[52:53]
	s_cbranch_execz .LBB0_395
	v_mul_f32_e32 v12, 0x3fb8aa3b, v12
	v_exp_f32_e32 v14, v12
	s_lshl_b64 s[18:19], s[4:5], 8
	v_lshl_add_u64 v[12:13], v[40:41], 0, s[18:19]
	global_store_dword v[12:13], v14, off
	s_branch .LBB0_395
